# scan prologue loads hoisted/pipelined with register renaming, step-loop waves run at s_setprio 1, DPP wave reduction in norm loops
# speedup vs baseline: 1.0175x; 1.0175x over previous
; __device__ __forceinline__ unsigned pk2(float lo, float hi) { const f2 v = {lo, hi}; return __builtin_bit_cast(unsigned, __builtin_convertvector(v, bf16x2_hw)); }
; __device__ __forceinline__ float shx(float v, int o, int lane) { return __builtin_bit_cast(float, __builtin_amdgcn_ds_bpermute((lane ^ o) << 2, __builtin_bit_cast(int, v))); }
; #define lane LANE_()
; __device__ __forceinline__ float wave_sum(float v, int lane) {
; #pragma unroll
;     for (int o = 1; o < 64; o <<= 1) v += shx(v, o, lane);
;     return v;
; }
; __device__ __forceinline__ void norm_phase(const float* xp, const float* xs, const float* g, const float* modl  , bf16* XN, int wave, int lane, int G) {
;     ...
;     for (int m = gw; m < MT; m += NGW) {
;         const float* xrow = m < MP ? xp + (size_t)m * D : xs + (size_t)(m - MP) * D;
;         const f32x4* xr = (const f32x4*)xrow + lane;
;         f32x4 v[4]; float s = 0.f;
; #pragma unroll
;         for (int j = 0; j < 4; ++j) { v[j] = xr[64 * j]; s += (v[j].x * v[j].x + v[j].y * v[j].y) + (v[j].z * v[j].z + v[j].w * v[j].w); }
;         const float rstd = __builtin_amdgcn_rsqf(wave_sum(s, lane) * (1.f / D) + NORM_EPS);
;         const float* mp = modl + (size_t)seq_of(m) * 12288;
;         unsigned long long* o8 = (unsigned long long*)(XN + (size_t)m * D) + lane;
; #pragma unroll
;         for (int j = 0; j < 4; ++j) { const f32x4 sh = ((const f32x4*)mp)[64 * j + lane], sc = ((const f32x4*)(mp + 1024))[64 * j + lane];
;             const f32x4 y = v[j] * rstd * gv[j] * (1.0f + sc) + sh;
;             o8[64 * j] = (unsigned long long)pk2(y.x, y.y) | ((unsigned long long)pk2(y.z, y.w) << 32); }
;     }
.LBB0_141:
	v_lshl_add_u64 v[38:39], s[64:65], 0, v[18:19]
	global_load_dwordx4 v[30:33], v[38:39], off offset:1024
	global_load_dwordx4 v[34:37], v[38:39], off offset:3072
	global_load_dwordx4 v[70:73], v[38:39], off offset:2048
	global_load_dwordx4 v[26:29], v[38:39], off
	s_nop 0
	s_nop 0
	s_nop 0
	s_nop 0
	s_lshr_b32 s14, s14, 12
	s_add_i32 s14, s14, 1
	s_and_b64 s[46:47], s[62:63], exec
	s_cselect_b32 s14, 0, s14
	s_mul_hi_u32 s24, s14, 0xc000
	s_mul_i32 s14, s14, 0xc000
	s_add_u32 s46, s3, s14
	s_addc_u32 s47, s27, s24
	v_lshl_add_u64 v[50:51], s[46:47], 0, v[18:19]
	global_load_dwordx4 v[46:49], v[50:51], off
	global_load_dwordx4 v[74:77], v[50:51], off offset:1024
	global_load_dwordx4 v[78:81], v[50:51], off offset:2048
	global_load_dwordx4 v[82:85], v[50:51], off offset:3072
	v_add_co_u32_e32 v42, vcc, s26, v50
	s_lshl_b64 s[46:47], s[60:61], 11
	s_nop 0
	v_addc_co_u32_e32 v43, vcc, 0, v51, vcc
	global_load_dwordx4 v[42:45], v[42:43], off
	s_nop 0
	s_nop 0
	s_add_u32 s4, s4, s10
	s_addc_u32 s5, s5, s11
	s_add_u32 s6, s6, s58
	s_addc_u32 s7, s7, s59
	s_cmp_lt_i32 s4, 0x14000
	s_waitcnt vmcnt(5)
	v_pk_mul_f32 v[52:53], v[28:29], v[28:29]
	v_pk_mul_f32 v[54:55], v[26:27], v[26:27]
	v_pk_mul_f32 v[56:57], v[32:33], v[32:33]
	v_pk_mul_f32 v[58:59], v[30:31], v[30:31]
	v_pk_mov_b32 v[64:65], v[54:55], v[52:53] op_sel:[1,0]
	v_mov_b32_e32 v55, v53
	v_pk_mov_b32 v[52:53], v[58:59], v[56:57] op_sel:[1,0]
	v_mov_b32_e32 v59, v57
	v_mul_f32_e32 v63, v34, v34
	v_mul_f32_e32 v60, v71, v71
	v_mul_f32_e32 v62, v73, v73
	v_pk_add_f32 v[54:55], v[64:65], v[54:55]
	v_pk_add_f32 v[52:53], v[52:53], v[58:59]
	v_mul_f32_e32 v66, v35, v35
	v_mul_f32_e32 v67, v36, v36
	v_mul_f32_e32 v68, v37, v37
	v_pk_fma_f32 v[56:57], v[70:71], v[70:71], v[60:61] op_sel_hi:[1,1,0]
	v_pk_fma_f32 v[60:61], v[72:73], v[72:73], v[62:63] op_sel_hi:[1,1,0]
	v_pk_add_f32 v[54:55], v[54:55], v[54:55] op_sel:[0,1] op_sel_hi:[1,0]
	v_pk_add_f32 v[52:53], v[52:53], v[52:53] op_sel:[0,1] op_sel_hi:[1,0]
	v_mov_b32_e32 v57, v67
	v_mov_b32_e32 v61, v68
	v_mov_b32_e32 v55, v63
	v_mov_b32_e32 v53, v66
	v_pk_add_f32 v[56:57], v[56:57], v[60:61]
	v_pk_add_f32 v[52:53], v[54:55], v[52:53]
	s_waitcnt vmcnt(0)
	v_pk_add_f32 v[44:45], v[44:45], 1.0 op_sel_hi:[1,0]
	v_pk_add_f32 v[52:53], v[52:53], v[56:57]
	v_pk_add_f32 v[42:43], v[42:43], 1.0 op_sel_hi:[1,0]
	v_add_f32_e32 v52, v52, v53
	v_lshl_add_u64 v[56:57], v[50:51], 0, s[20:21]
	global_load_dwordx4 v[58:61], v[56:57], off offset:1024
	global_load_dwordx4 v[62:65], v[56:57], off offset:2048
	global_load_dwordx4 v[66:69], v[56:57], off offset:3072
	s_nop 1
	v_add_f32_dpp v52, v52, v52 quad_perm:[1,0,3,2] row_mask:0xf bank_mask:0xf
	s_nop 1
	v_add_f32_dpp v52, v52, v52 quad_perm:[2,3,0,1] row_mask:0xf bank_mask:0xf
	s_nop 1
	v_add_f32_dpp v52, v52, v52 row_half_mirror row_mask:0xf bank_mask:0xf
	s_nop 1
	v_add_f32_dpp v52, v52, v52 row_mirror row_mask:0xf bank_mask:0xf
	s_nop 1
	v_add_f32_dpp v52, v52, v52 row_bcast:15 row_mask:0xa bank_mask:0xf
	s_nop 1
	v_add_f32_dpp v52, v52, v52 row_bcast:31 row_mask:0xc bank_mask:0xf
	s_nop 1
	v_readlane_b32 s98, v52, 63
	s_nop 1
	v_mov_b32_e32 v54, s98
	v_lshl_add_u64 v[52:53], v[16:17], 0, s[46:47]
	v_fmamk_f32 v54, v54, 0x3a800000, v218
	v_rsq_f32_e32 v54, v54
	s_nop 0
	v_pk_mul_f32 v[28:29], v[28:29], v[54:55] op_sel_hi:[1,0]
	v_pk_mul_f32 v[26:27], v[26:27], v[54:55] op_sel_hi:[1,0]
	v_pk_mul_f32 v[28:29], v[2:3], v[28:29]
	v_pk_mul_f32 v[26:27], v[0:1], v[26:27]
	v_pk_fma_f32 v[28:29], v[44:45], v[28:29], v[48:49]
	v_pk_fma_f32 v[26:27], v[42:43], v[26:27], v[46:47]
	v_pk_mul_f32 v[32:33], v[32:33], v[54:55] op_sel_hi:[1,0]
	v_cvt_pk_bf16_f32 v26, v26, v27
	v_cvt_pk_bf16_f32 v27, v28, v29
	global_store_dwordx2 v[52:53], v[26:27], off
	s_nop 0
	s_nop 0
	s_nop 0
	v_pk_mul_f32 v[30:31], v[30:31], v[54:55] op_sel_hi:[1,0]
	v_pk_mul_f32 v[32:33], v[6:7], v[32:33]
	v_pk_mul_f32 v[30:31], v[4:5], v[30:31]
	v_pk_mul_f32 v[40:41], v[72:73], v[54:55] op_sel_hi:[1,0]
	v_pk_mul_f32 v[38:39], v[70:71], v[54:55] op_sel_hi:[1,0]
	v_pk_mul_f32 v[40:41], v[10:11], v[40:41]
	v_pk_mul_f32 v[38:39], v[8:9], v[38:39]
	v_pk_mul_f32 v[36:37], v[36:37], v[54:55] op_sel_hi:[1,0]
	v_pk_mul_f32 v[34:35], v[34:35], v[54:55] op_sel_hi:[1,0]
	v_pk_mul_f32 v[36:37], v[14:15], v[36:37]
	v_pk_mul_f32 v[34:35], v[12:13], v[34:35]
	s_waitcnt vmcnt(3)
	v_pk_add_f32 v[28:29], v[60:61], 1.0 op_sel_hi:[1,0]
	v_pk_add_f32 v[26:27], v[58:59], 1.0 op_sel_hi:[1,0]
	v_pk_fma_f32 v[28:29], v[28:29], v[32:33], v[76:77]
	v_pk_fma_f32 v[26:27], v[26:27], v[30:31], v[74:75]
	s_nop 0
	v_cvt_pk_bf16_f32 v26, v26, v27
	v_cvt_pk_bf16_f32 v27, v28, v29
	global_store_dwordx2 v[52:53], v[26:27], off offset:512
	s_nop 0
	s_nop 0
	s_nop 0
	s_waitcnt vmcnt(3)
	v_pk_add_f32 v[28:29], v[64:65], 1.0 op_sel_hi:[1,0]
	v_pk_add_f32 v[26:27], v[62:63], 1.0 op_sel_hi:[1,0]
	v_pk_fma_f32 v[28:29], v[28:29], v[40:41], v[80:81]
	v_pk_fma_f32 v[26:27], v[26:27], v[38:39], v[78:79]
	s_nop 0
	v_cvt_pk_bf16_f32 v26, v26, v27
	v_cvt_pk_bf16_f32 v27, v28, v29
	global_store_dwordx2 v[52:53], v[26:27], off offset:1024
	s_nop 0
	s_nop 0
	s_nop 0
	s_waitcnt vmcnt(3)
	v_pk_add_f32 v[28:29], v[68:69], 1.0 op_sel_hi:[1,0]
	v_pk_add_f32 v[26:27], v[66:67], 1.0 op_sel_hi:[1,0]
	v_pk_fma_f32 v[28:29], v[36:37], v[28:29], v[84:85]
	v_pk_fma_f32 v[26:27], v[34:35], v[26:27], v[82:83]
	s_nop 0
	v_cvt_pk_bf16_f32 v26, v26, v27
	v_cvt_pk_bf16_f32 v27, v28, v29
	global_store_dwordx2 v[52:53], v[26:27], off offset:1536
	s_cbranch_scc0 .LBB0_146

; #define lane LANE_()
; template <int MODE>
; __device__ __forceinline__ void scan_prologue(const ScanP& P, int m0, int seqbase, int T, int h, int d, float* slab, LAS float* lw, float* bon, int lane) {
;     const int fr = lane & 15, fq = lane >> 4, m = m0 + fr, pos = m - seqbase; const bool hp = pos > 0, hn = pos < T - 1;
;     float* srow = slab + fr * 384;
;     f32x4 k4[4], kk4[4], r4[4]; float ss = 0.f;
;     v2u pk_[4][3], pv_[4][3], pr_[4][3];
;     const int offp_ = hp ? -PRP : 0, offn_ = hn ? PRP : 0; const unsigned mp_ = hp ? 0xffffffffu : 0u, mn_ = hn ? 0xffffffffu : 0u;
; #pragma unroll
;     for (int n = 0; n < 4; ++n) { const bf16* p = P.proj + (size_t)m * PRP + h * 64 + 16 * n + 4 * fq;
;         { v2u t; pk_[n][1] = *(const v2u*)(p + 512);
;           t = *(const v2u*)(p + 512 + offp_); pk_[n][0] = (v2u){t.x & mp_, t.y & mp_};
;           t = *(const v2u*)(p + 512 + offn_); pk_[n][2] = (v2u){t.x & mn_, t.y & mn_};
;           if (MODE != 1) { pv_[n][1] = *(const v2u*)(p + 1024);
;             t = *(const v2u*)(p + 1024 + offp_); pv_[n][0] = (v2u){t.x & mp_, t.y & mp_};
;             t = *(const v2u*)(p + 1024 + offn_); pv_[n][2] = (v2u){t.x & mn_, t.y & mn_}; }
;           if (MODE == 2) { pr_[n][1] = *(const v2u*)(p);
;             t = *(const v2u*)(p + offp_); pr_[n][0] = (v2u){t.x & mp_, t.y & mp_};
;             t = *(const v2u*)(p + offn_); pr_[n][2] = (v2u){t.x & mn_, t.y & mn_}; } } }
; template <int MODE>
; __device__ __forceinline__ void scan_item(const CAS Args* A, int l, int item, float* slab0, LAS float* ldsw, int lane) {
;     ...
;     for (int sc = 0; sc < nsub; ++sc) {
;         const int sub = d ? nsub - 1 - sc : sc, t0 = m0c + sub * 16;
;         float* slab = slab0;
;         { int lane_l = lane; asm volatile("" : "+v"(lane_l)); scan_prologue<MODE>(P, t0, seqbase, T, h, d, slab, ldsw, bon, lane_l);
.LBB0_288:
	s_setprio 0
	s_add_i32 s61, s61, 1
	s_cmp_eq_u32 s61, s53
	s_cbranch_scc1 .LBB0_286
.LBB0_289:
	s_not_b32 s4, s61
	s_add_i32 s14, s53, s4
	s_and_b64 s[4:5], s[82:83], exec
	s_cselect_b32 s4, s61, s14
	s_lshl_b32 s4, s4, 4
	v_mov_b32_e32 v212, v172
	s_add_i32 s4, s4, s52
	s_lshl_b32 s14, s87, 1
	v_and_b32_e32 v231, 15, v212
	v_or_b32_e32 v128, s4, v231
	s_waitcnt vmcnt(0)
	v_subrev_u32_e32 v129, s86, v128
	v_cmp_lt_i32_e64 s[4:5], 0, v129
	v_cmp_gt_i32_e32 vcc, s49, v129
	v_ashrrev_i32_e32 v129, 31, v128
	v_ashrrev_i32_e32 v138, 4, v212
	v_lshlrev_b64 v[128:129], 12, v[128:129]
	v_lshl_add_u64 v[128:129], s[64:65], 0, v[128:129]
	v_lshlrev_b32_e32 v154, 2, v138
	v_lshl_add_u64 v[132:133], v[128:129], 0, s[14:15]
	v_ashrrev_i32_e32 v155, 31, v154
	v_cndmask_b32_e64 v131, 0, -1, s[4:5]
	v_cndmask_b32_e64 v130, 0, v224, s[4:5]
	v_lshl_add_u64 v[132:133], v[154:155], 1, v[132:133]
	v_lshl_add_u64 v[130:131], v[132:133], 0, v[130:131]
	global_load_dwordx2 v[134:135], v[130:131], off offset:1024
	global_load_dwordx2 v[166:167], v[132:133], off offset:2048
	global_load_dwordx2 v[140:141], v[130:131], off offset:2048
	global_load_dwordx2 v[156:157], v[132:133], off offset:1056
	global_load_dwordx2 v[142:143], v[130:131], off offset:1056
	global_load_dwordx2 v[254:255], v[132:133], off offset:2080
	global_load_dwordx2 v[146:147], v[130:131], off offset:2080
	global_load_dwordx2 v[150:151], v[130:131], off offset:1088
	global_load_dwordx2 v[160:161], v[130:131], off offset:2112
	global_load_dwordx2 v[184:185], v[130:131], off offset:1120
	global_load_dwordx2 v[204:205], v[130:131], off offset:2144
	global_load_dwordx2 v[170:171], v[132:133], off offset:1024
	s_nop 0
	v_cndmask_b32_e32 v180, 0, v219, vcc
	v_mul_u32_u24_e32 v158, 0x180, v231
	s_mov_b32 s85, s15
	v_lshlrev_b32_e32 v164, 3, v138
	v_lshl_add_u64 v[128:129], v[128:129], 0, s[84:85]
	v_ashrrev_i32_e32 v165, 31, v164
	s_mov_b32 s91, 15
	s_waitcnt vmcnt(0)
	v_lshlrev_b32_e32 v240, 16, v170
	v_cndmask_b32_e64 v230, 0, v134, s[4:5]
	v_cndmask_b32_e64 v234, 0, v135, s[4:5]
	v_lshl_add_u64 v[134:135], v[132:133], 0, v[180:181]
	global_load_dwordx2 v[138:139], v[134:135], off offset:2048
	global_load_dwordx2 v[144:145], v[134:135], off offset:1056
	global_load_dwordx2 v[148:149], v[134:135], off offset:2080
	global_load_dwordx2 v[152:153], v[134:135], off offset:1088
	global_load_dwordx2 v[162:163], v[134:135], off offset:2112
	global_load_dwordx2 v[186:187], v[134:135], off offset:1120
	global_load_dwordx2 v[206:207], v[134:135], off offset:2144
	global_load_dwordx2 v[136:137], v[134:135], off offset:1024
	v_lshlrev_b32_e32 v180, 2, v158
	v_lshl_add_u32 v158, v212, 4, s94
	v_lshl_add_u64 v[176:177], s[62:63], 0, v[180:181]
	v_add_u32_e32 v180, 0x2400, v158
	v_add_u32_e32 v158, s87, v154
	v_ashrrev_i32_e32 v159, 31, v158
	v_lshlrev_b64 v[168:169], 2, v[158:159]
	v_lshl_add_u64 v[158:159], s[8:9], 0, v[168:169]
	v_and_b32_e32 v241, 0xffff0000, v170
	v_lshlrev_b32_e32 v170, 16, v171
	v_and_b32_e32 v171, 0xffff0000, v171
	v_lshlrev_b32_e32 v232, 16, v230
	v_and_b32_e32 v233, 0xffff0000, v230
	v_lshlrev_b32_e32 v238, 16, v234
	v_and_b32_e32 v239, 0xffff0000, v234
	v_lshl_add_u64 v[176:177], v[154:155], 2, v[176:177]
	v_and_b32_e32 v154, -16, v212
	v_add_u32_e32 v234, s94, v154
	v_add_u32_e32 v154, 0x2000, v234
	s_waitcnt vmcnt(0)
	v_cndmask_b32_e32 v237, 0, v136, vcc
	v_cndmask_b32_e32 v242, 0, v137, vcc
	s_nop 0
	s_nop 0
	v_cndmask_b32_e64 v203, 0, v140, s[4:5]
	v_cndmask_b32_e64 v202, 0, v141, s[4:5]
	s_nop 0
	v_lshlrev_b32_e32 v246, 16, v202
	v_and_b32_e32 v247, 0xffff0000, v202
	v_lshlrev_b32_e32 v202, 16, v166
	v_cndmask_b32_e32 v195, 0, v138, vcc
	v_cndmask_b32_e32 v193, 0, v139, vcc
	s_nop 0
	s_nop 0
	v_cndmask_b32_e64 v201, 0, v142, s[4:5]
	v_cndmask_b32_e64 v200, 0, v143, s[4:5]
	s_nop 0
	v_lshlrev_b32_e32 v250, 16, v200
	v_and_b32_e32 v251, 0xffff0000, v200
	v_lshlrev_b32_e32 v200, 16, v156
	v_cndmask_b32_e32 v194, 0, v144, vcc
	v_cndmask_b32_e32 v192, 0, v145, vcc
	s_nop 0
	s_nop 0
	v_cndmask_b32_e64 v189, 0, v146, s[4:5]
	v_cndmask_b32_e64 v188, 0, v147, s[4:5]
	global_load_dwordx2 v[146:147], v[132:133], off offset:2112
	s_nop 0
	v_cndmask_b32_e32 v179, 0, v148, vcc
	v_cndmask_b32_e32 v178, 0, v149, vcc
	global_load_dwordx2 v[148:149], v[132:133], off offset:1088
	s_nop 0
	v_cndmask_b32_e64 v199, 0, v150, s[4:5]
	v_cndmask_b32_e64 v198, 0, v151, s[4:5]
	global_load_dwordx2 v[150:151], v[132:133], off offset:1120
	s_nop 0
	v_cndmask_b32_e32 v191, 0, v152, vcc
	v_cndmask_b32_e32 v190, 0, v153, vcc
	global_load_dwordx2 v[152:153], v[132:133], off offset:2144
	s_nop 0
	s_nop 0
	v_cndmask_b32_e64 v197, 0, v160, s[4:5]
	v_cndmask_b32_e64 v196, 0, v161, s[4:5]
	s_nop 0
	v_cndmask_b32_e32 v183, 0, v162, vcc
	v_cndmask_b32_e32 v182, 0, v163, vcc
	s_nop 0
	s_nop 0
	v_cndmask_b32_e64 v214, 0, v184, s[4:5]
	v_cndmask_b32_e64 v213, 0, v185, s[4:5]
	s_nop 0
	s_nop 0
	s_nop 0
	s_nop 0
	v_lshl_add_u64 v[132:133], v[164:165], 1, v[128:129]
	global_load_dwordx4 v[140:143], v[132:133], off offset:3072
	global_load_dwordx4 v[136:139], v[132:133], off offset:3328
	global_load_dwordx4 v[128:131], v[132:133], off offset:3136
	v_cndmask_b32_e32 v216, 0, v186, vcc
	v_cndmask_b32_e64 v229, 0, v204, s[4:5]
	v_cndmask_b32_e64 v217, 0, v205, s[4:5]
	s_nop 0
	v_add_co_u32_e64 v160, s[4:5], s45, v158
	v_cndmask_b32_e32 v215, 0, v187, vcc
	global_load_dwordx4 v[184:187], v[158:159], off offset:2048
	s_nop 0
	v_addc_co_u32_e64 v161, s[4:5], 0, v159, s[4:5]
	v_add_co_u32_e64 v162, s[4:5], s96, v158
	v_cndmask_b32_e32 v236, 0, v206, vcc
	v_cndmask_b32_e32 v235, 0, v207, vcc
	global_load_dwordx4 v[204:207], v[160:161], off
	s_nop 0
	s_nop 0
	s_nop 0
	s_nop 0
	global_load_dwordx4 v[132:135], v[132:133], off offset:3392
	s_nop 0
	s_nop 0
	v_addc_co_u32_e64 v163, s[4:5], 0, v159, s[4:5]
	global_load_dwordx4 v[208:211], v[162:163], off offset:2048
	v_cmp_eq_u32_e32 vcc, s88, v231
	s_waitcnt vmcnt(2)
; #define LAS __attribute__((address_space(3)))
; #define lane LANE_()
; template <int MODE>
; __device__ __forceinline__ void scan_prologue(const ScanP& P, int m0, int seqbase, int T, int h, int d, float* slab, LAS float* lw, float* bon, int lane) {
;     ...
; #pragma unroll
;     for (int n = 0; n < 4; ++n) { const int c = 16 * n + 4 * fq, col = h * 64 + c;
;         k4[n] = CONV3_(pk_, 1);
;         if (MODE != 1) { const f32x4 v4 = CONV3_(pv_, 2); *(f32x4*)(srow + 320 + c) = v4; LAS float* xsel = (fr == (d ? 15 : 0)) ? lw + 2048 + c : lw + 2304 + lane * 4; *(LAS f32x4*)(xsel + 192) = v4; }
;         if (MODE == 2) { r4[n] = CONV3_(pr_, 0); *(LAS f32x4*)(lw + 1024 + fr * 64 + c) = r4[n]; }
;         kk4[n] = k4[n] * *(const f32x4*)(P.k_k + col);
;         ss += (kk4[n].x * kk4[n].x + kk4[n].y * kk4[n].y) + (kk4[n].z * kk4[n].z + kk4[n].w * kk4[n].w); }
	v_pk_mul_f32 v[170:171], v[206:207], v[170:171]
	v_pk_mul_f32 v[204:205], v[204:205], v[240:241]
	v_pk_fma_f32 v[170:171], v[186:187], v[238:239], v[170:171]
	v_pk_fma_f32 v[184:185], v[184:185], v[232:233], v[204:205]
	v_lshlrev_b32_e32 v204, 16, v242
	v_and_b32_e32 v205, 0xffff0000, v242
	v_lshlrev_b32_e32 v186, 16, v237
	v_and_b32_e32 v187, 0xffff0000, v237
	s_waitcnt vmcnt(0)
	v_pk_fma_f32 v[204:205], v[210:211], v[204:205], v[170:171]
	v_lshl_add_u64 v[170:171], s[80:81], 0, v[168:169]
	v_pk_fma_f32 v[206:207], v[208:209], v[186:187], v[184:185]
	global_load_dwordx4 v[208:211], v[170:171], off
	v_add_co_u32_e64 v184, s[4:5], s26, v170
	s_nop 0
	s_nop 0
	v_addc_co_u32_e64 v185, s[4:5], 0, v171, s[4:5]
	global_load_dwordx4 v[238:241], v[184:185], off offset:2048
	v_add_co_u32_e64 v186, s[4:5], s96, v170
	v_lshlrev_b32_e32 v232, 16, v203
	s_nop 0
	v_addc_co_u32_e64 v187, s[4:5], 0, v171, s[4:5]
	global_load_dwordx4 v[242:245], v[186:187], off
	v_and_b32_e32 v233, 0xffff0000, v203
	v_and_b32_e32 v203, 0xffff0000, v166
	v_lshlrev_b32_e32 v166, 16, v167
	v_and_b32_e32 v167, 0xffff0000, v167
	s_mov_b32 s4, 0
	s_waitcnt vmcnt(1)
	v_pk_mul_f32 v[166:167], v[240:241], v[166:167]
	v_pk_mul_f32 v[202:203], v[238:239], v[202:203]
	v_pk_fma_f32 v[166:167], v[210:211], v[246:247], v[166:167]
	global_load_dwordx4 v[246:249], v[162:163], off offset:2112
	v_pk_fma_f32 v[202:203], v[208:209], v[232:233], v[202:203]
	v_lshlrev_b32_e32 v208, 16, v195
	v_and_b32_e32 v209, 0xffff0000, v195
	v_lshlrev_b32_e32 v210, 16, v193
	v_and_b32_e32 v211, 0xffff0000, v193
	s_waitcnt vmcnt(1)
	v_pk_fma_f32 v[210:211], v[244:245], v[210:211], v[166:167]
	v_pk_fma_f32 v[208:209], v[242:243], v[208:209], v[202:203]
	global_load_dwordx4 v[242:245], v[160:161], off offset:64
	s_nop 0
	global_store_dwordx4 v[176:177], v[208:211], off offset:1280
	v_cndmask_b32_e32 v233, v180, v154, vcc
	v_lshl_add_u64 v[154:155], s[72:73], 0, v[168:169]
	global_load_dwordx4 v[238:241], v[154:155], off
	ds_write_b128 v233, v[208:211] offset:768
	v_and_b32_e32 v195, 0xffff0000, v192
	s_waitcnt vmcnt(0)
	v_pk_mul_f32 v[208:209], v[204:205], v[240:241]
	v_pk_mul_f32 v[210:211], v[206:207], v[238:239]
	v_pk_mul_f32 v[166:167], v[208:209], v[208:209]
	v_pk_mul_f32 v[202:203], v[210:211], v[210:211]
	s_nop 0
	v_pk_mov_b32 v[238:239], v[202:203], v[166:167] op_sel:[1,0]
	v_mov_b32_e32 v203, v167
	v_pk_add_f32 v[166:167], v[238:239], v[202:203]
	global_load_dwordx4 v[238:241], v[158:159], off offset:2112
	s_nop 0
	s_nop 0
	v_lshlrev_b32_e32 v202, 16, v201
	v_and_b32_e32 v203, 0xffff0000, v201
	v_and_b32_e32 v201, 0xffff0000, v156
	v_lshlrev_b32_e32 v156, 16, v157
	v_and_b32_e32 v157, 0xffff0000, v157
	v_pk_mul_f32 v[156:157], v[244:245], v[156:157]
	v_pk_mul_f32 v[200:201], v[242:243], v[200:201]
	global_load_dwordx4 v[242:245], v[186:187], off offset:64
	s_waitcnt vmcnt(1)
	v_pk_fma_f32 v[156:157], v[240:241], v[250:251], v[156:157]
	v_pk_fma_f32 v[200:201], v[238:239], v[202:203], v[200:201]
	global_load_dwordx4 v[238:241], v[184:185], off offset:2112
	v_lshlrev_b32_e32 v202, 16, v194
	v_and_b32_e32 v203, 0xffff0000, v194
	v_lshlrev_b32_e32 v194, 16, v192
	v_pk_fma_f32 v[192:193], v[248:249], v[194:195], v[156:157]
	global_load_dwordx4 v[248:251], v[170:171], off offset:64
	v_pk_fma_f32 v[194:195], v[246:247], v[202:203], v[200:201]
	s_nop 0
	s_nop 0
	s_nop 0
	v_lshlrev_b32_e32 v156, 16, v189
	v_and_b32_e32 v157, 0xffff0000, v189
	v_lshlrev_b32_e32 v246, 16, v188
	v_and_b32_e32 v247, 0xffff0000, v188
	v_lshlrev_b32_e32 v188, 16, v254
	v_and_b32_e32 v189, 0xffff0000, v254
	v_lshlrev_b32_e32 v144, 16, v255
	v_and_b32_e32 v145, 0xffff0000, v255
	s_waitcnt vmcnt(1)
	v_pk_mul_f32 v[144:145], v[240:241], v[144:145]
	v_pk_mul_f32 v[188:189], v[238:239], v[188:189]
	global_load_dwordx4 v[238:241], v[154:155], off offset:64
	s_waitcnt vmcnt(1)
	v_pk_fma_f32 v[144:145], v[250:251], v[246:247], v[144:145]
	v_pk_fma_f32 v[156:157], v[248:249], v[156:157], v[188:189]
	global_load_dwordx4 v[246:249], v[162:163], off offset:2176
	v_lshlrev_b32_e32 v188, 16, v179
	v_and_b32_e32 v189, 0xffff0000, v179
	v_lshlrev_b32_e32 v200, 16, v178
	v_and_b32_e32 v201, 0xffff0000, v178
	v_pk_fma_f32 v[202:203], v[244:245], v[200:201], v[144:145]
	v_pk_fma_f32 v[200:201], v[242:243], v[188:189], v[156:157]
	global_load_dwordx4 v[242:245], v[160:161], off offset:128
	s_nop 0
	global_store_dwordx4 v[176:177], v[200:203], off offset:1344
	s_nop 0
	v_add_u32_e32 v144, 0x2040, v234
	v_cndmask_b32_e32 v232, v180, v144, vcc
	ds_write_b128 v232, v[200:203] offset:768
	s_waitcnt vmcnt(3)
	v_pk_mul_f32 v[200:201], v[192:193], v[240:241]
	v_pk_mul_f32 v[202:203], v[194:195], v[238:239]
	global_load_dwordx4 v[238:241], v[158:159], off offset:2176
	s_nop 0
	s_nop 0
	v_pk_mul_f32 v[144:145], v[200:201], v[200:201]
	v_pk_mul_f32 v[156:157], v[202:203], v[202:203]
	s_nop 0
	v_pk_mov_b32 v[178:179], v[156:157], v[144:145] op_sel:[1,0]
	v_mov_b32_e32 v157, v145
	v_pk_add_f32 v[250:251], v[178:179], v[156:157]
	v_lshlrev_b32_e32 v178, 16, v148
	v_and_b32_e32 v179, 0xffff0000, v148
	v_lshlrev_b32_e32 v148, 16, v149
	v_and_b32_e32 v149, 0xffff0000, v149
	v_lshlrev_b32_e32 v144, 16, v199
	v_and_b32_e32 v145, 0xffff0000, v199
	v_lshlrev_b32_e32 v156, 16, v198
	v_and_b32_e32 v157, 0xffff0000, v198
	s_waitcnt vmcnt(2)
	v_pk_mul_f32 v[148:149], v[244:245], v[148:149]
	v_pk_mul_f32 v[178:179], v[242:243], v[178:179]
	global_load_dwordx4 v[242:245], v[184:185], off offset:2176
	s_waitcnt vmcnt(1)
; #define LAS __attribute__((address_space(3)))
; __device__ __forceinline__ float shx(float v, int o, int lane) { return __builtin_bit_cast(float, __builtin_amdgcn_ds_bpermute((lane ^ o) << 2, __builtin_bit_cast(int, v))); }
; #define lane LANE_()
; template <int MODE>
; __device__ __forceinline__ void scan_prologue(const ScanP& P, int m0, int seqbase, int T, int h, int d, float* slab, LAS float* lw, float* bon, int lane) {
;     ...
; #pragma unroll
;     for (int n = 0; n < 4; ++n) { const int c = 16 * n + 4 * fq, col = h * 64 + c;
;         k4[n] = CONV3_(pk_, 1);
;         if (MODE != 1) { const f32x4 v4 = CONV3_(pv_, 2); *(f32x4*)(srow + 320 + c) = v4; LAS float* xsel = (fr == (d ? 15 : 0)) ? lw + 2048 + c : lw + 2304 + lane * 4; *(LAS f32x4*)(xsel + 192) = v4; }
;         if (MODE == 2) { r4[n] = CONV3_(pr_, 0); *(LAS f32x4*)(lw + 1024 + fr * 64 + c) = r4[n]; }
;         kk4[n] = k4[n] * *(const f32x4*)(P.k_k + col);
;         ss += (kk4[n].x * kk4[n].x + kk4[n].y * kk4[n].y) + (kk4[n].z * kk4[n].z + kk4[n].w * kk4[n].w); }
;     ...
;     ss += shx(ss, 16, lane); ss += shx(ss, 32, lane);
	v_pk_fma_f32 v[148:149], v[240:241], v[156:157], v[148:149]
	v_pk_fma_f32 v[144:145], v[238:239], v[144:145], v[178:179]
	global_load_dwordx4 v[238:241], v[170:171], off offset:128
	v_lshlrev_b32_e32 v156, 16, v191
	v_and_b32_e32 v157, 0xffff0000, v191
	v_lshlrev_b32_e32 v178, 16, v190
	v_and_b32_e32 v179, 0xffff0000, v190
	v_pk_fma_f32 v[188:189], v[248:249], v[178:179], v[148:149]
	v_pk_fma_f32 v[190:191], v[246:247], v[156:157], v[144:145]
	global_load_dwordx4 v[246:249], v[186:187], off offset:128
	s_nop 0
	s_nop 0
	s_nop 0
	v_lshlrev_b32_e32 v156, 16, v146
	v_and_b32_e32 v157, 0xffff0000, v146
	v_lshlrev_b32_e32 v146, 16, v147
	v_and_b32_e32 v147, 0xffff0000, v147
	v_lshlrev_b32_e32 v144, 16, v197
	v_and_b32_e32 v145, 0xffff0000, v197
	v_lshlrev_b32_e32 v148, 16, v196
	v_and_b32_e32 v149, 0xffff0000, v196
	v_lshlrev_b32_e32 v178, 16, v213
	v_and_b32_e32 v179, 0xffff0000, v213
	s_waitcnt vmcnt(2)
	v_pk_mul_f32 v[146:147], v[244:245], v[146:147]
	v_pk_mul_f32 v[156:157], v[242:243], v[156:157]
	global_load_dwordx4 v[242:245], v[154:155], off offset:128
	s_waitcnt vmcnt(2)
	v_pk_fma_f32 v[146:147], v[240:241], v[148:149], v[146:147]
	v_pk_fma_f32 v[144:145], v[238:239], v[144:145], v[156:157]
	global_load_dwordx4 v[238:241], v[158:159], off offset:2240
	v_lshlrev_b32_e32 v148, 16, v183
	v_and_b32_e32 v149, 0xffff0000, v183
	v_lshlrev_b32_e32 v156, 16, v182
	v_and_b32_e32 v157, 0xffff0000, v182
	s_waitcnt vmcnt(2)
	v_pk_fma_f32 v[146:147], v[248:249], v[156:157], v[146:147]
	v_pk_fma_f32 v[144:145], v[246:247], v[148:149], v[144:145]
	global_load_dwordx4 v[246:249], v[160:161], off offset:192
	v_add_u32_e32 v148, 0x2080, v234
	global_store_dwordx4 v[176:177], v[144:147], off offset:1408
	v_cndmask_b32_e32 v230, v180, v148, vcc
	ds_write_b128 v230, v[144:147] offset:768
	s_nop 0
	v_lshlrev_b32_e32 v182, 16, v150
	v_and_b32_e32 v183, 0xffff0000, v150
	v_lshlrev_b32_e32 v150, 16, v151
	v_and_b32_e32 v151, 0xffff0000, v151
	v_lshlrev_b32_e32 v148, 16, v214
	v_and_b32_e32 v149, 0xffff0000, v214
	s_waitcnt vmcnt(3)
	v_pk_mul_f32 v[196:197], v[188:189], v[244:245]
	v_pk_mul_f32 v[198:199], v[190:191], v[242:243]
	global_load_dwordx4 v[242:245], v[162:163], off offset:2240
	s_nop 0
	s_nop 0
	s_nop 0
	s_nop 0
	s_nop 0
	s_waitcnt vmcnt(2)
	v_pk_mul_f32 v[150:151], v[248:249], v[150:151]
	v_pk_mul_f32 v[156:157], v[246:247], v[182:183]
	global_load_dwordx4 v[246:249], v[170:171], off offset:192
	v_pk_fma_f32 v[146:147], v[240:241], v[178:179], v[150:151]
	v_pk_fma_f32 v[144:145], v[238:239], v[148:149], v[156:157]
	global_load_dwordx4 v[238:241], v[184:185], off offset:2240
	global_load_dwordx4 v[156:159], v[186:187], off offset:192
	v_lshlrev_b32_e32 v148, 16, v216
	v_and_b32_e32 v149, 0xffff0000, v216
	v_lshlrev_b32_e32 v150, 16, v215
	v_and_b32_e32 v151, 0xffff0000, v215
	s_waitcnt vmcnt(3)
	v_pk_fma_f32 v[178:179], v[244:245], v[150:151], v[146:147]
	v_pk_fma_f32 v[182:183], v[242:243], v[148:149], v[144:145]
	global_load_dwordx4 v[242:245], v[154:155], off offset:192
	s_nop 0
	s_nop 0
	s_nop 0
	v_lshlrev_b32_e32 v170, 16, v152
	v_and_b32_e32 v171, 0xffff0000, v152
	v_lshlrev_b32_e32 v152, 16, v153
	v_and_b32_e32 v153, 0xffff0000, v153
	v_lshlrev_b32_e32 v160, 16, v229
	v_and_b32_e32 v161, 0xffff0000, v229
	v_lshlrev_b32_e32 v162, 16, v217
	v_and_b32_e32 v163, 0xffff0000, v217
	s_waitcnt vmcnt(2)
	v_pk_mul_f32 v[150:151], v[240:241], v[152:153]
	v_pk_mul_f32 v[148:149], v[238:239], v[170:171]
	v_pk_fma_f32 v[146:147], v[248:249], v[162:163], v[150:151]
	v_pk_fma_f32 v[144:145], v[246:247], v[160:161], v[148:149]
	v_lshlrev_b32_e32 v148, 16, v236
	v_and_b32_e32 v149, 0xffff0000, v236
	v_lshlrev_b32_e32 v150, 16, v235
	v_and_b32_e32 v151, 0xffff0000, v235
	s_waitcnt vmcnt(1)
	v_pk_fma_f32 v[146:147], v[158:159], v[150:151], v[146:147]
	v_pk_fma_f32 v[144:145], v[156:157], v[148:149], v[144:145]
	v_add_u32_e32 v148, 0x20c0, v234
	global_store_dwordx4 v[176:177], v[144:147], off offset:1472
	v_cndmask_b32_e32 v229, v180, v148, vcc
	ds_write_b128 v229, v[144:147] offset:768
	s_nop 0
	v_lshl_or_b32 v180, v231, 6, s89
	s_waitcnt vmcnt(1)
	v_pk_mul_f32 v[186:187], v[182:183], v[242:243]
	v_pk_mul_f32 v[184:185], v[178:179], v[244:245]
	v_mul_f32_e32 v146, v186, v186
	v_pk_add_f32 v[144:145], v[166:167], v[166:167] op_sel:[0,1] op_sel_hi:[1,0]
	v_mul_f32_e32 v148, v187, v187
	v_mov_b32_e32 v145, v146
	v_pk_add_f32 v[146:147], v[250:251], v[250:251] op_sel:[0,1] op_sel_hi:[1,0]
	v_mul_f32_e32 v149, v184, v184
	v_mov_b32_e32 v147, v148
	v_pk_add_f32 v[144:145], v[144:145], v[146:147]
	v_mul_f32_e32 v146, v199, v199
	v_pk_fma_f32 v[146:147], v[198:199], v[198:199], v[146:147] op_sel_hi:[1,1,0]
	v_mul_f32_e32 v148, v197, v197
	v_mul_f32_e32 v150, v185, v185
	v_mov_b32_e32 v147, v149
	v_pk_fma_f32 v[148:149], v[196:197], v[196:197], v[148:149] op_sel_hi:[1,1,0]
	s_nop 0
	v_mov_b32_e32 v149, v150
	v_pk_add_f32 v[146:147], v[146:147], v[148:149]
	s_nop 0
	v_pk_add_f32 v[144:145], v[144:145], v[146:147]
	s_nop 0
	v_add_f32_e32 v144, v144, v145
	v_lshlrev_b32_e32 v145, 2, v212
	v_xor_b32_e32 v146, 64, v145
	ds_bpermute_b32 v146, v146, v144
	v_xor_b32_e32 v145, 0x80, v145
	s_waitcnt lgkmcnt(0)
	v_add_f32_e32 v144, v144, v146
	ds_bpermute_b32 v145, v145, v144
	s_waitcnt lgkmcnt(0)
; __device__ __forceinline__ unsigned pk2(float lo, float hi) { const f2 v = {lo, hi}; return __builtin_bit_cast(unsigned, __builtin_convertvector(v, bf16x2_hw)); }
; __device__ __forceinline__ float tanhf_(float x) { return 1.0f - 2.0f * __builtin_amdgcn_rcpf(1.0f + __builtin_amdgcn_exp2f(2.8853900817779268f * x)); }
; template <int MODE>
; __device__ __forceinline__ void scan_prologue(const ScanP& P, int m0, int seqbase, int T, int h, int d, float* slab, LAS float* lw, float* bon, int lane) {
;     ...
;     const float rs = __builtin_amdgcn_rsqf(ss + 1e-12f);
;     f32x4 Dw[4], Da[4];
; #pragma unroll
;     for (int n = 0; n < 4; ++n) { Dw[n] = (f32x4){0.f, 0.f, 0.f, 0.f}; Da[n] = (f32x4){0.f, 0.f, 0.f, 0.f}; }
; #pragma unroll
;     for (int ks = 0; ks < 2; ++ks) {
;         const v4u xw = xw_[ks]; const bf16x8 xa = xa_[ks];
;         v4u tw;
; #pragma unroll
;         for (int e = 0; e < 4; ++e) tw[e] = pk2(tanhf_(bflo(xw[e])), tanhf_(bfhi(xw[e])));
;         const bf16x8 twv = __builtin_bit_cast(bf16x8, tw);
; #pragma unroll
;         for (int n = 0; n < 4; ++n) { const size_t wo = (size_t)(h * 64 + 16 * n + fr) * 64 + ks * 32 + 8 * fq;
;             Dw[n] = __builtin_amdgcn_mfma_f32_16x16x32_bf16(*(const bf16x8*)(P.upw + wo), twv, Dw[n], 0, 0, 0);
;             Da[n] = __builtin_amdgcn_mfma_f32_16x16x32_bf16(*(const bf16x8*)(P.upa + wo), xa, Da[n], 0, 0, 0); }
;     }
	v_add_f32_e32 v144, v144, v145
	v_add_f32_e32 v212, 0x2b8cbccc, v144
	v_lshlrev_b32_e32 v144, 16, v140
	v_and_b32_e32 v140, 0xffff0000, v140
	v_mul_f32_e32 v140, 0x4038aa3b, v140
	v_exp_f32_e32 v140, v140
	v_mul_f32_e32 v144, 0x4038aa3b, v144
	v_exp_f32_e32 v144, v144
	v_add_f32_e32 v140, 1.0, v140
	v_rcp_f32_e32 v145, v140
	v_lshlrev_b32_e32 v140, 16, v141
	v_and_b32_e32 v141, 0xffff0000, v141
	v_mul_f32_e32 v140, 0x4038aa3b, v140
	v_mul_f32_e32 v141, 0x4038aa3b, v141
	v_exp_f32_e32 v140, v140
	v_exp_f32_e32 v141, v141
	v_add_f32_e32 v144, 1.0, v144
	v_rcp_f32_e32 v144, v144
	v_add_f32_e32 v140, 1.0, v140
	v_add_f32_e32 v141, 1.0, v141
	v_rcp_f32_e32 v140, v140
	v_rcp_f32_e32 v141, v141
	v_pk_fma_f32 v[144:145], v[144:145], 2.0, 1.0 op_sel_hi:[1,0,0] neg_lo:[1,0,0] neg_hi:[1,0,0]
	v_pk_fma_f32 v[140:141], v[140:141], 2.0, 1.0 op_sel_hi:[1,0,0] neg_lo:[1,0,0] neg_hi:[1,0,0]
	s_nop 0
	v_cvt_pk_bf16_f32 v153, v140, v141
	v_lshlrev_b32_e32 v140, 16, v142
	v_and_b32_e32 v141, 0xffff0000, v142
	v_mul_f32_e32 v140, 0x4038aa3b, v140
	v_mul_f32_e32 v141, 0x4038aa3b, v141
	v_exp_f32_e32 v140, v140
	v_exp_f32_e32 v141, v141
	v_cvt_pk_bf16_f32 v152, v144, v145
	v_add_f32_e32 v140, 1.0, v140
	v_add_f32_e32 v141, 1.0, v141
	v_rcp_f32_e32 v140, v140
	v_rcp_f32_e32 v141, v141
	s_nop 0
	v_pk_fma_f32 v[140:141], v[140:141], 2.0, 1.0 op_sel_hi:[1,0,0] neg_lo:[1,0,0] neg_hi:[1,0,0]
	s_nop 0
	v_cvt_pk_bf16_f32 v154, v140, v141
	v_lshlrev_b32_e32 v140, 16, v143
	v_and_b32_e32 v141, 0xffff0000, v143
	v_mul_f32_e32 v140, 0x4038aa3b, v140
	v_mul_f32_e32 v141, 0x4038aa3b, v141
	v_exp_f32_e32 v140, v140
	v_exp_f32_e32 v141, v141
	v_add_f32_e32 v140, 1.0, v140
	v_add_f32_e32 v141, 1.0, v141
	v_rcp_f32_e32 v140, v140
	v_rcp_f32_e32 v141, v141
	s_nop 0
	v_pk_fma_f32 v[140:141], v[140:141], 2.0, 1.0 op_sel_hi:[1,0,0] neg_lo:[1,0,0] neg_hi:[1,0,0]
	s_nop 0
	v_cvt_pk_bf16_f32 v155, v140, v141
	v_lshl_add_u64 v[140:141], v[180:181], 0, v[164:165]
	v_lshlrev_b64 v[144:145], 1, v[140:141]
	v_lshl_add_u64 v[170:171], s[78:79], 0, v[144:145]
	global_load_dwordx4 v[246:249], v[170:171], off
	global_load_dwordx4 v[156:159], v[170:171], off offset:2048
	s_waitcnt vmcnt(0)
	v_mfma_f32_16x16x32_bf16 v[160:163], v[156:159], v[136:139], 0
	v_or_b32_e32 v156, 0x800, v180
	v_mov_b32_e32 v157, v181
	v_lshl_add_u64 v[156:157], v[156:157], 0, v[164:165]
	v_lshlrev_b64 v[236:237], 1, v[156:157]
	v_lshl_add_u64 v[166:167], s[74:75], 0, v[144:145]
	global_load_dwordx4 v[140:143], v[166:167], off
	global_load_dwordx4 v[148:151], v[166:167], off offset:2048
	v_lshl_add_u64 v[156:157], s[74:75], 0, v[236:237]
	global_load_dwordx4 v[144:147], v[156:157], off
	s_nop 0
	s_nop 0
	s_nop 0
	s_nop 0
	s_nop 0
	s_waitcnt vmcnt(0)
	v_mfma_f32_16x16x32_bf16 v[214:217], v[144:147], v[152:155], 0
	v_lshl_add_u64 v[156:157], s[78:79], 0, v[236:237]
	global_load_dwordx4 v[156:159], v[156:157], off
	s_waitcnt vmcnt(0)
	v_mfma_f32_16x16x32_bf16 v[236:239], v[156:159], v[136:139], 0
	v_or_b32_e32 v156, 0xc00, v180
	v_mov_b32_e32 v157, v181
	v_lshl_add_u64 v[156:157], v[156:157], 0, v[164:165]
	v_lshlrev_b64 v[244:245], 1, v[156:157]
	v_lshl_add_u64 v[156:157], s[74:75], 0, v[244:245]
	global_load_dwordx4 v[156:159], v[156:157], off
	v_mfma_f32_16x16x32_bf16 v[140:143], v[140:143], v[152:155], 0
	v_mfma_f32_16x16x32_bf16 v[148:151], v[148:151], v[152:155], 0
	s_waitcnt vmcnt(0)
	v_mfma_f32_16x16x32_bf16 v[240:243], v[156:159], v[152:155], 0
	global_load_dwordx4 v[156:159], v[166:167], off offset:64
	v_lshl_add_u64 v[152:153], s[78:79], 0, v[244:245]
	global_load_dwordx4 v[152:155], v[152:153], off
	v_mfma_f32_16x16x32_bf16 v[144:147], v[246:249], v[136:139], 0
	global_load_dwordx4 v[248:251], v[170:171], off offset:64
	s_waitcnt vmcnt(1)
	v_mfma_f32_16x16x32_bf16 v[244:247], v[152:155], v[136:139], 0
	v_lshlrev_b32_e32 v136, 16, v128
	v_and_b32_e32 v128, 0xffff0000, v128
	v_mul_f32_e32 v136, 0x4038aa3b, v136
	v_mul_f32_e32 v128, 0x4038aa3b, v128
	v_exp_f32_e32 v136, v136
	v_exp_f32_e32 v128, v128
	v_add_f32_e32 v136, 1.0, v136
	v_add_f32_e32 v128, 1.0, v128
	v_rcp_f32_e32 v136, v136
	v_rcp_f32_e32 v137, v128
	s_nop 0
	v_pk_fma_f32 v[136:137], v[136:137], 2.0, 1.0 op_sel_hi:[1,0,0] neg_lo:[1,0,0] neg_hi:[1,0,0]
	s_nop 0
	v_cvt_pk_bf16_f32 v128, v136, v137
	v_lshlrev_b32_e32 v136, 16, v129
	v_and_b32_e32 v129, 0xffff0000, v129
	v_mul_f32_e32 v136, 0x4038aa3b, v136
	v_mul_f32_e32 v129, 0x4038aa3b, v129
	v_exp_f32_e32 v136, v136
	v_exp_f32_e32 v129, v129
	v_add_f32_e32 v136, 1.0, v136
	v_add_f32_e32 v129, 1.0, v129
	v_rcp_f32_e32 v136, v136
	v_rcp_f32_e32 v137, v129
	s_nop 0
	v_pk_fma_f32 v[136:137], v[136:137], 2.0, 1.0 op_sel_hi:[1,0,0] neg_lo:[1,0,0] neg_hi:[1,0,0]
	s_nop 0
	v_cvt_pk_bf16_f32 v129, v136, v137
	v_lshlrev_b32_e32 v136, 16, v130
	v_and_b32_e32 v130, 0xffff0000, v130
	v_mul_f32_e32 v136, 0x4038aa3b, v136
	v_mul_f32_e32 v130, 0x4038aa3b, v130
	v_exp_f32_e32 v136, v136
	v_exp_f32_e32 v130, v130
	v_add_f32_e32 v136, 1.0, v136
	v_add_f32_e32 v130, 1.0, v130
	v_rcp_f32_e32 v136, v136
	v_rcp_f32_e32 v137, v130
	s_nop 0
	v_pk_fma_f32 v[136:137], v[136:137], 2.0, 1.0 op_sel_hi:[1,0,0] neg_lo:[1,0,0] neg_hi:[1,0,0]
	s_nop 0
	v_cvt_pk_bf16_f32 v130, v136, v137
	v_lshlrev_b32_e32 v136, 16, v131
	v_and_b32_e32 v131, 0xffff0000, v131
	v_mul_f32_e32 v136, 0x4038aa3b, v136
	v_mul_f32_e32 v131, 0x4038aa3b, v131
	v_exp_f32_e32 v136, v136
	v_exp_f32_e32 v131, v131
	v_add_f32_e32 v136, 1.0, v136
	v_add_f32_e32 v131, 1.0, v131
	v_rcp_f32_e32 v136, v136
	v_rcp_f32_e32 v137, v131
	s_nop 0
	v_pk_fma_f32 v[136:137], v[136:137], 2.0, 1.0 op_sel_hi:[1,0,0] neg_lo:[1,0,0] neg_hi:[1,0,0]
	s_nop 0
	v_cvt_pk_bf16_f32 v131, v136, v137
	global_load_dwordx4 v[136:139], v[166:167], off offset:2112
	s_nop 0
	v_mfma_f32_16x16x32_bf16 v[152:155], v[156:159], v[128:131], v[140:143]
	global_load_dwordx4 v[140:143], v[170:171], off offset:2112
	s_nop 0
	s_waitcnt vmcnt(2)
; #define LAS __attribute__((address_space(3)))
; __device__ __forceinline__ unsigned pk2(float lo, float hi) { const f2 v = {lo, hi}; return __builtin_bit_cast(unsigned, __builtin_convertvector(v, bf16x2_hw)); }
; __device__ __forceinline__ float sigmoidf_(float x) { return __builtin_amdgcn_rcpf(1.0f + __builtin_amdgcn_exp2f(-1.4426950408889634f * x)); }
; __device__ __forceinline__ float tanhf_(float x) { return 1.0f - 2.0f * __builtin_amdgcn_rcpf(1.0f + __builtin_amdgcn_exp2f(2.8853900817779268f * x)); }
; template <int MODE>
; __device__ __forceinline__ void scan_prologue(const ScanP& P, int m0, int seqbase, int T, int h, int d, float* slab, LAS float* lw, float* bon, int lane) {
;     ...
; #pragma unroll
;     for (int ks = 0; ks < 2; ++ks) {
;         const v4u xw = xw_[ks]; const bf16x8 xa = xa_[ks];
;         v4u tw;
; #pragma unroll
;         for (int e = 0; e < 4; ++e) tw[e] = pk2(tanhf_(bflo(xw[e])), tanhf_(bfhi(xw[e])));
;         const bf16x8 twv = __builtin_bit_cast(bf16x8, tw);
; #pragma unroll
;         for (int n = 0; n < 4; ++n) { const size_t wo = (size_t)(h * 64 + 16 * n + fr) * 64 + ks * 32 + 8 * fq;
;             Dw[n] = __builtin_amdgcn_mfma_f32_16x16x32_bf16(*(const bf16x8*)(P.upw + wo), twv, Dw[n], 0, 0, 0);
;             Da[n] = __builtin_amdgcn_mfma_f32_16x16x32_bf16(*(const bf16x8*)(P.upa + wo), xa, Da[n], 0, 0, 0); }
;     }
;     float bp = 0.f;
; #pragma unroll
;     for (int n = 0; n < 4; ++n) { const int c = 16 * n + 4 * fq, col = h * 64 + c;
;         const f32x4 w0 = *(const f32x4*)(P.w0 + col), a0 = *(const f32x4*)(P.a0 + col), ka = *(const f32x4*)(P.k_a + col);
;         f32x4 wv, bv, kd, av;
; #pragma unroll
;         for (int i = 0; i < 4; ++i) { const float ic = sigmoidf_(Da[n][i] + a0[i]);
;             wv[i] = __builtin_amdgcn_exp2f(-DECAY_SCALE * 1.4426950408889634f * sigmoidf_(Dw[n][i] + w0[i]));
;             const float kk = kk4[n][i] * rs; av[i] = -kk; bv[i] = kk * ic; kd[i] = k4[n][i] * (1.0f + (ic - 1.0f) * ka[i]); }
;         *(LAS f32x4*)(lw + fr * 64 + c) = av; *(LAS f32x4*)(lw + 3072 + fr * 64 + c) = wv; *(LAS f32x4*)(lw + (MODE == 3 ? 1024 : 4096) + fr * 64 + c) = bv;
	v_mfma_f32_16x16x32_bf16 v[156:159], v[248:251], v[132:135], v[144:147]
	s_nop 0
	s_waitcnt vmcnt(1)
	v_mfma_f32_16x16x32_bf16 v[144:147], v[136:139], v[128:131], v[148:151]
	s_nop 0
	s_waitcnt vmcnt(0)
	v_mfma_f32_16x16x32_bf16 v[148:151], v[140:143], v[132:135], v[160:163]
	v_or_b32_e32 v136, 0x820, v180
	v_mov_b32_e32 v137, v181
	v_or_b32_e32 v180, 0xc20, v180
	v_lshl_add_u64 v[136:137], v[136:137], 0, v[164:165]
	v_lshl_add_u64 v[160:161], v[180:181], 0, v[164:165]
	v_lshlrev_b64 v[140:141], 1, v[136:137]
	v_lshlrev_b64 v[164:165], 1, v[160:161]
	v_lshl_add_u64 v[136:137], s[74:75], 0, v[140:141]
	global_load_dwordx4 v[248:251], v[136:137], off
	v_lshl_add_u64 v[160:161], s[74:75], 0, v[164:165]
	s_nop 0
	v_lshl_add_u64 v[140:141], s[78:79], 0, v[140:141]
	global_load_dwordx4 v[160:163], v[160:161], off
	v_rsq_f32_e32 v180, v212
	global_load_dwordx4 v[140:143], v[140:141], off
	s_waitcnt vmcnt(2)
	v_mfma_f32_16x16x32_bf16 v[136:139], v[248:251], v[128:131], v[214:217]
	s_nop 2
	v_lshl_add_u64 v[214:215], s[76:77], 0, v[168:169]
	global_load_dwordx4 v[248:251], v[214:215], off
	v_lshl_add_u64 v[212:213], s[10:11], 0, v[168:169]
	v_lshl_add_u64 v[216:217], s[6:7], 0, v[168:169]
	global_load_dwordx4 v[168:171], v[216:217], off
	s_waitcnt vmcnt(3)
	v_mfma_f32_16x16x32_bf16 v[128:131], v[160:163], v[128:131], v[240:243]
	global_load_dwordx4 v[240:243], v[212:213], off
	v_lshl_add_u64 v[160:161], s[78:79], 0, v[164:165]
	global_load_dwordx4 v[160:163], v[160:161], off
	s_nop 0
	s_nop 0
	s_waitcnt vmcnt(4)
	v_mfma_f32_16x16x32_bf16 v[140:143], v[140:143], v[132:135], v[236:239]
	global_load_dwordx4 v[236:239], v[216:217], off offset:64
	s_nop 0
	s_waitcnt vmcnt(4)
	v_add_f32_e32 v156, v156, v248
	s_waitcnt vmcnt(1)
	v_mfma_f32_16x16x32_bf16 v[132:135], v[160:163], v[132:135], v[244:247]
	global_load_dwordx4 v[244:247], v[214:215], off offset:64
	s_nop 0
	v_add_f32_e32 v158, v158, v250
	v_mul_f32_e32 v156, 0xbfb8aa3b, v156
	v_mul_f32_e32 v158, 0xbfb8aa3b, v158
	v_exp_f32_e32 v156, v156
	v_exp_f32_e32 v158, v158
	v_add_f32_e32 v156, 1.0, v156
	v_add_f32_e32 v158, 1.0, v158
	v_rcp_f32_e32 v164, v156
	v_add_f32_e32 v156, v157, v249
	v_rcp_f32_e32 v166, v158
	v_add_f32_e32 v158, v159, v251
	global_load_dwordx4 v[248:251], v[212:213], off offset:64
	v_mul_f32_e32 v156, 0xbfb8aa3b, v156
	v_mul_f32_e32 v158, 0xbfb8aa3b, v158
	v_exp_f32_e32 v156, v156
	v_exp_f32_e32 v158, v158
	v_add_f32_e32 v156, 1.0, v156
	v_add_f32_e32 v158, 1.0, v158
	v_rcp_f32_e32 v165, v156
	v_rcp_f32_e32 v167, v158
	v_add_f32_e32 v152, v152, v240
	v_add_f32_e32 v153, v153, v241
	v_add_f32_e32 v154, v154, v242
	v_add_f32_e32 v155, v155, v243
	global_load_dwordx4 v[240:243], v[212:213], off offset:128
	v_mul_f32_e32 v152, 0xbfb8aa3b, v152
	v_mul_f32_e32 v153, 0xbfb8aa3b, v153
	v_mul_f32_e32 v154, 0xbfb8aa3b, v154
	v_mul_f32_e32 v155, 0xbfb8aa3b, v155
	v_exp_f32_e32 v152, v152
	v_exp_f32_e32 v153, v153
	v_exp_f32_e32 v154, v154
	v_exp_f32_e32 v155, v155
	v_add_f32_e32 v152, 1.0, v152
	v_add_f32_e32 v153, 1.0, v153
	v_add_f32_e32 v154, 1.0, v154
	v_add_f32_e32 v155, 1.0, v155
	v_rcp_f32_e32 v152, v152
	v_rcp_f32_e32 v153, v153
	v_rcp_f32_e32 v154, v154
	v_rcp_f32_e32 v155, v155
	v_mul_f32_e32 v152, 0xbf60028a, v152
	v_mul_f32_e32 v153, 0xbf60028a, v153
	v_pk_mul_f32 v[160:161], v[210:211], v[180:181] op_sel_hi:[1,0]
	v_mul_f32_e32 v154, 0xbf60028a, v154
	v_mul_f32_e32 v155, 0xbf60028a, v155
	v_pk_mul_f32 v[162:163], v[208:209], v[180:181] op_sel_hi:[1,0]
	global_load_dwordx4 v[208:211], v[214:215], off offset:128
	v_exp_f32_e32 v152, v152
	v_exp_f32_e32 v153, v153
	v_xor_b32_e32 v157, 0x80000000, v161
	v_xor_b32_e32 v156, 0x80000000, v160
	v_exp_f32_e32 v154, v154
	v_exp_f32_e32 v155, v155
	v_xor_b32_e32 v158, 0x80000000, v162
	v_xor_b32_e32 v159, 0x80000000, v163
	v_pk_mul_f32 v[160:161], v[160:161], v[164:165]
	v_pk_mul_f32 v[162:163], v[162:163], v[166:167]
	v_pk_add_f32 v[166:167], v[166:167], -1.0 op_sel_hi:[1,0]
	v_pk_add_f32 v[164:165], v[164:165], -1.0 op_sel_hi:[1,0]
	v_pk_fma_f32 v[166:167], v[170:171], v[166:167], 1.0 op_sel_hi:[1,1,0]
	v_pk_fma_f32 v[164:165], v[168:169], v[164:165], 1.0 op_sel_hi:[1,1,0]
	v_pk_mul_f32 v[168:169], v[204:205], v[166:167]
	v_pk_mul_f32 v[166:167], v[206:207], v[164:165]
	global_load_dwordx4 v[204:207], v[216:217], off offset:128
	v_lshl_add_u32 v164, v231, 8, v234
	ds_write_b128 v164, v[156:159]
	ds_write_b128 v164, v[152:155] offset:12288
	ds_write_b128 v164, v[160:163] offset:4096
	global_store_dwordx4 v[176:177], v[166:169], off offset:768
	ds_write_b128 v233, v[166:169] offset:512
	global_load_dwordx4 v[166:169], v[216:217], off offset:192
	s_nop 0
	s_nop 0
	s_nop 0
	s_waitcnt vmcnt(6)
	v_add_f32_e32 v148, v148, v244
	s_waitcnt vmcnt(5)
; #define LAS __attribute__((address_space(3)))
; __device__ __forceinline__ float sigmoidf_(float x) { return __builtin_amdgcn_rcpf(1.0f + __builtin_amdgcn_exp2f(-1.4426950408889634f * x)); }
; #define lane LANE_()
; template <int MODE>
; __device__ __forceinline__ void scan_prologue(const ScanP& P, int m0, int seqbase, int T, int h, int d, float* slab, LAS float* lw, float* bon, int lane) {
;     ...
;     for (int n = 0; n < 4; ++n) { const int c = 16 * n + 4 * fq, col = h * 64 + c;
;         const f32x4 w0 = *(const f32x4*)(P.w0 + col), a0 = *(const f32x4*)(P.a0 + col), ka = *(const f32x4*)(P.k_a + col);
;         f32x4 wv, bv, kd, av;
; #pragma unroll
;         for (int i = 0; i < 4; ++i) { const float ic = sigmoidf_(Da[n][i] + a0[i]);
;             wv[i] = __builtin_amdgcn_exp2f(-DECAY_SCALE * 1.4426950408889634f * sigmoidf_(Dw[n][i] + w0[i]));
;             const float kk = kk4[n][i] * rs; av[i] = -kk; bv[i] = kk * ic; kd[i] = k4[n][i] * (1.0f + (ic - 1.0f) * ka[i]); }
;         *(LAS f32x4*)(lw + fr * 64 + c) = av; *(LAS f32x4*)(lw + 3072 + fr * 64 + c) = wv; *(LAS f32x4*)(lw + (MODE == 3 ? 1024 : 4096) + fr * 64 + c) = bv;
;         if (MODE != 1) *(f32x4*)(srow + 192 + c) = kd;
;         { LAS float* xsel = (fr == (d ? 15 : 0)) ? lw + 2048 + c : lw + 2304 + lane * 4;
;           if (MODE != 1) *(LAS f32x4*)(xsel + 128) = kd; }
;         if (MODE == 2) { const f32x4 rk = *(const f32x4*)(P.r_k + col); const f32x4 t = r4[n] * kd * rk; bp += (t.x + t.y) + (t.z + t.w); }
;         if ((n & 1) == 1) asm volatile("" ::: "memory");
	v_add_f32_e32 v144, v144, v248
	v_add_f32_e32 v145, v145, v249
	v_add_f32_e32 v146, v146, v250
	v_add_f32_e32 v147, v147, v251
	global_load_dwordx4 v[248:251], v[214:215], off offset:192
	v_mul_f32_e32 v144, 0xbfb8aa3b, v144
	v_add_f32_e32 v149, v149, v245
	v_mul_f32_e32 v145, 0xbfb8aa3b, v145
	v_add_f32_e32 v150, v150, v246
	v_mul_f32_e32 v146, 0xbfb8aa3b, v146
	v_add_f32_e32 v151, v151, v247
	global_load_dwordx4 v[244:247], v[212:213], off offset:192
	v_mul_f32_e32 v147, 0xbfb8aa3b, v147
	v_mul_f32_e32 v148, 0xbfb8aa3b, v148
	v_exp_f32_e32 v144, v144
	v_mul_f32_e32 v149, 0xbfb8aa3b, v149
	v_exp_f32_e32 v145, v145
	v_mul_f32_e32 v150, 0xbfb8aa3b, v150
	v_exp_f32_e32 v146, v146
	v_mul_f32_e32 v151, 0xbfb8aa3b, v151
	v_exp_f32_e32 v147, v147
	v_exp_f32_e32 v148, v148
	v_exp_f32_e32 v149, v149
	v_exp_f32_e32 v150, v150
	v_exp_f32_e32 v151, v151
	v_add_f32_e32 v144, 1.0, v144
	v_add_f32_e32 v145, 1.0, v145
	v_add_f32_e32 v146, 1.0, v146
	v_add_f32_e32 v147, 1.0, v147
	v_add_f32_e32 v148, 1.0, v148
	v_rcp_f32_e32 v144, v144
	v_add_f32_e32 v149, 1.0, v149
	v_rcp_f32_e32 v145, v145
	v_add_f32_e32 v150, 1.0, v150
	v_rcp_f32_e32 v146, v146
	v_add_f32_e32 v151, 1.0, v151
	v_rcp_f32_e32 v147, v147
	v_rcp_f32_e32 v148, v148
	v_rcp_f32_e32 v149, v149
	v_rcp_f32_e32 v150, v150
	v_rcp_f32_e32 v151, v151
	v_mul_f32_e32 v144, 0xbf60028a, v144
	v_mul_f32_e32 v145, 0xbf60028a, v145
	v_pk_mul_f32 v[160:161], v[202:203], v[180:181] op_sel_hi:[1,0]
	v_mul_f32_e32 v146, 0xbf60028a, v146
	v_mul_f32_e32 v147, 0xbf60028a, v147
	v_pk_mul_f32 v[162:163], v[200:201], v[180:181] op_sel_hi:[1,0]
	v_exp_f32_e32 v144, v144
	v_exp_f32_e32 v145, v145
	v_xor_b32_e32 v157, 0x80000000, v161
	v_xor_b32_e32 v156, 0x80000000, v160
	v_exp_f32_e32 v146, v146
	v_exp_f32_e32 v147, v147
	v_xor_b32_e32 v158, 0x80000000, v162
	v_xor_b32_e32 v159, 0x80000000, v163
	v_pk_mul_f32 v[160:161], v[160:161], v[148:149]
	v_pk_mul_f32 v[162:163], v[162:163], v[150:151]
	v_pk_add_f32 v[150:151], v[150:151], -1.0 op_sel_hi:[1,0]
	v_pk_add_f32 v[148:149], v[148:149], -1.0 op_sel_hi:[1,0]
	v_pk_fma_f32 v[150:151], v[238:239], v[150:151], 1.0 op_sel_hi:[1,1,0]
	v_pk_fma_f32 v[148:149], v[236:237], v[148:149], 1.0 op_sel_hi:[1,1,0]
	v_pk_mul_f32 v[150:151], v[192:193], v[150:151]
	v_pk_mul_f32 v[148:149], v[194:195], v[148:149]
	ds_write_b128 v164, v[156:159] offset:64
	ds_write_b128 v164, v[144:147] offset:12352
	ds_write_b128 v164, v[160:163] offset:4160
	global_store_dwordx4 v[176:177], v[148:151], off offset:832
	ds_write_b128 v232, v[148:151] offset:512
	s_nop 0
	s_nop 0
	s_nop 0
	s_waitcnt vmcnt(7)
	v_add_f32_e32 v136, v136, v240
	s_waitcnt vmcnt(6)
	v_add_f32_e32 v140, v140, v208
	v_add_f32_e32 v142, v142, v210
	v_mul_f32_e32 v140, 0xbfb8aa3b, v140
	v_mul_f32_e32 v142, 0xbfb8aa3b, v142
	v_exp_f32_e32 v140, v140
	v_exp_f32_e32 v142, v142
	v_add_f32_e32 v137, v137, v241
	v_add_f32_e32 v138, v138, v242
	v_add_f32_e32 v140, 1.0, v140
	v_add_f32_e32 v142, 1.0, v142
	v_add_f32_e32 v139, v139, v243
	v_rcp_f32_e32 v152, v140
	v_mul_f32_e32 v136, 0xbfb8aa3b, v136
	v_add_f32_e32 v140, v141, v209
	v_mul_f32_e32 v137, 0xbfb8aa3b, v137
	v_rcp_f32_e32 v154, v142
	v_mul_f32_e32 v138, 0xbfb8aa3b, v138
	v_add_f32_e32 v142, v143, v211
	v_mul_f32_e32 v139, 0xbfb8aa3b, v139
	v_exp_f32_e32 v136, v136
	v_mul_f32_e32 v140, 0xbfb8aa3b, v140
	v_exp_f32_e32 v137, v137
	v_exp_f32_e32 v138, v138
	v_mul_f32_e32 v142, 0xbfb8aa3b, v142
	v_exp_f32_e32 v139, v139
	v_exp_f32_e32 v140, v140
	v_exp_f32_e32 v142, v142
	v_add_f32_e32 v136, 1.0, v136
	v_add_f32_e32 v137, 1.0, v137
	v_add_f32_e32 v138, 1.0, v138
	v_add_f32_e32 v139, 1.0, v139
	v_rcp_f32_e32 v136, v136
	v_add_f32_e32 v140, 1.0, v140
	v_rcp_f32_e32 v137, v137
	v_rcp_f32_e32 v138, v138
	v_add_f32_e32 v142, 1.0, v142
	v_rcp_f32_e32 v139, v139
	v_rcp_f32_e32 v153, v140
	v_rcp_f32_e32 v155, v142
	v_mul_f32_e32 v136, 0xbf60028a, v136
	v_mul_f32_e32 v137, 0xbf60028a, v137
	v_pk_mul_f32 v[148:149], v[198:199], v[180:181] op_sel_hi:[1,0]
	v_mul_f32_e32 v138, 0xbf60028a, v138
	v_mul_f32_e32 v139, 0xbf60028a, v139
	v_pk_mul_f32 v[150:151], v[196:197], v[180:181] op_sel_hi:[1,0]
	v_exp_f32_e32 v136, v136
	v_exp_f32_e32 v137, v137
	v_xor_b32_e32 v141, 0x80000000, v149
	v_xor_b32_e32 v140, 0x80000000, v148
	v_exp_f32_e32 v138, v138
	v_exp_f32_e32 v139, v139
	v_xor_b32_e32 v142, 0x80000000, v150
	v_xor_b32_e32 v143, 0x80000000, v151
	v_pk_mul_f32 v[148:149], v[148:149], v[152:153]
	v_pk_mul_f32 v[150:151], v[150:151], v[154:155]
	v_pk_add_f32 v[154:155], v[154:155], -1.0 op_sel_hi:[1,0]
	v_pk_add_f32 v[152:153], v[152:153], -1.0 op_sel_hi:[1,0]
	s_waitcnt vmcnt(5)
; #define LAS __attribute__((address_space(3)))
; __device__ __forceinline__ float sigmoidf_(float x) { return __builtin_amdgcn_rcpf(1.0f + __builtin_amdgcn_exp2f(-1.4426950408889634f * x)); }
; #define LDS_WAIT() asm volatile("s_waitcnt lgkmcnt(0)" ::: "memory")
; #define lane LANE_()
; template <int MODE>
; __device__ __forceinline__ void scan_prologue(const ScanP& P, int m0, int seqbase, int T, int h, int d, float* slab, LAS float* lw, float* bon, int lane) {
;     ...
;     for (int n = 0; n < 4; ++n) { const int c = 16 * n + 4 * fq, col = h * 64 + c;
;         const f32x4 w0 = *(const f32x4*)(P.w0 + col), a0 = *(const f32x4*)(P.a0 + col), ka = *(const f32x4*)(P.k_a + col);
;         f32x4 wv, bv, kd, av;
; #pragma unroll
;         for (int i = 0; i < 4; ++i) { const float ic = sigmoidf_(Da[n][i] + a0[i]);
;             wv[i] = __builtin_amdgcn_exp2f(-DECAY_SCALE * 1.4426950408889634f * sigmoidf_(Dw[n][i] + w0[i]));
;             const float kk = kk4[n][i] * rs; av[i] = -kk; bv[i] = kk * ic; kd[i] = k4[n][i] * (1.0f + (ic - 1.0f) * ka[i]); }
;         *(LAS f32x4*)(lw + fr * 64 + c) = av; *(LAS f32x4*)(lw + 3072 + fr * 64 + c) = wv; *(LAS f32x4*)(lw + (MODE == 3 ? 1024 : 4096) + fr * 64 + c) = bv;
;         if (MODE != 1) *(f32x4*)(srow + 192 + c) = kd;
;         { LAS float* xsel = (fr == (d ? 15 : 0)) ? lw + 2048 + c : lw + 2304 + lane * 4;
;           if (MODE != 1) *(LAS f32x4*)(xsel + 128) = kd; }
;         if (MODE == 2) { const f32x4 rk = *(const f32x4*)(P.r_k + col); const f32x4 t = r4[n] * kd * rk; bp += (t.x + t.y) + (t.z + t.w); }
;         if ((n & 1) == 1) asm volatile("" ::: "memory");
;     }
; template <int MODE>
; __device__ __forceinline__ void scan_item(const CAS Args* A, int l, int item, float* slab0, LAS float* ldsw, int lane) {
;     ...
;         LDS_WAIT();
;         float nw[1], nb[1], nk[1], nv[1];
;         { const LAS float* xl = ldsw + 2048 + lane; nw[0] = 0.f; nb[0] = 0.f; nk[0] = 0.f; nv[0] = 0.f; if (MODE != 1) { nk[0] = xl[128]; nv[0] = xl[192]; } }
	v_pk_fma_f32 v[146:147], v[206:207], v[154:155], 1.0 op_sel_hi:[1,1,0]
	v_pk_fma_f32 v[144:145], v[204:205], v[152:153], 1.0 op_sel_hi:[1,1,0]
	v_pk_mul_f32 v[146:147], v[188:189], v[146:147]
	v_pk_mul_f32 v[144:145], v[190:191], v[144:145]
	ds_write_b128 v164, v[140:143] offset:128
	ds_write_b128 v164, v[136:139] offset:12416
	ds_write_b128 v164, v[148:151] offset:4224
	global_store_dwordx4 v[176:177], v[144:147], off offset:896
	ds_write_b128 v230, v[144:147] offset:512
	s_nop 0
	s_nop 0
	s_nop 0
	s_waitcnt vmcnt(3)
	v_add_f32_e32 v132, v132, v248
	s_waitcnt vmcnt(2)
	v_add_f32_e32 v128, v128, v244
	v_add_f32_e32 v129, v129, v245
	v_add_f32_e32 v130, v130, v246
	v_add_f32_e32 v131, v131, v247
	v_mul_f32_e32 v128, 0xbfb8aa3b, v128
	v_add_f32_e32 v133, v133, v249
	v_mul_f32_e32 v129, 0xbfb8aa3b, v129
	v_add_f32_e32 v134, v134, v250
	v_mul_f32_e32 v130, 0xbfb8aa3b, v130
	v_add_f32_e32 v135, v135, v251
	v_mul_f32_e32 v131, 0xbfb8aa3b, v131
	v_mul_f32_e32 v132, 0xbfb8aa3b, v132
	v_exp_f32_e32 v128, v128
	v_mul_f32_e32 v133, 0xbfb8aa3b, v133
	v_exp_f32_e32 v129, v129
	v_mul_f32_e32 v134, 0xbfb8aa3b, v134
	v_exp_f32_e32 v130, v130
	v_mul_f32_e32 v135, 0xbfb8aa3b, v135
	v_exp_f32_e32 v131, v131
	v_exp_f32_e32 v132, v132
	v_exp_f32_e32 v133, v133
	v_exp_f32_e32 v134, v134
	v_exp_f32_e32 v135, v135
	v_add_f32_e32 v128, 1.0, v128
	v_add_f32_e32 v129, 1.0, v129
	v_add_f32_e32 v130, 1.0, v130
	v_add_f32_e32 v131, 1.0, v131
	v_add_f32_e32 v132, 1.0, v132
	v_rcp_f32_e32 v128, v128
	v_add_f32_e32 v133, 1.0, v133
	v_rcp_f32_e32 v129, v129
	v_add_f32_e32 v134, 1.0, v134
	v_rcp_f32_e32 v130, v130
	v_add_f32_e32 v135, 1.0, v135
	v_rcp_f32_e32 v131, v131
	v_rcp_f32_e32 v132, v132
	v_rcp_f32_e32 v133, v133
	v_rcp_f32_e32 v134, v134
	v_rcp_f32_e32 v135, v135
	v_mul_f32_e32 v128, 0xbf60028a, v128
	v_mul_f32_e32 v129, 0xbf60028a, v129
	v_pk_mul_f32 v[144:145], v[186:187], v[180:181] op_sel_hi:[1,0]
	v_mul_f32_e32 v130, 0xbf60028a, v130
	v_mul_f32_e32 v131, 0xbf60028a, v131
	v_pk_mul_f32 v[146:147], v[184:185], v[180:181] op_sel_hi:[1,0]
	v_exp_f32_e32 v128, v128
	v_exp_f32_e32 v129, v129
	v_xor_b32_e32 v141, 0x80000000, v145
	v_xor_b32_e32 v140, 0x80000000, v144
	v_exp_f32_e32 v130, v130
	v_exp_f32_e32 v131, v131
	v_xor_b32_e32 v142, 0x80000000, v146
	v_xor_b32_e32 v143, 0x80000000, v147
	v_pk_mul_f32 v[144:145], v[144:145], v[132:133]
	v_pk_mul_f32 v[146:147], v[146:147], v[134:135]
	v_pk_add_f32 v[134:135], v[134:135], -1.0 op_sel_hi:[1,0]
	v_pk_add_f32 v[132:133], v[132:133], -1.0 op_sel_hi:[1,0]
	v_pk_fma_f32 v[134:135], v[168:169], v[134:135], 1.0 op_sel_hi:[1,1,0]
	v_pk_fma_f32 v[132:133], v[166:167], v[132:133], 1.0 op_sel_hi:[1,1,0]
	v_pk_mul_f32 v[134:135], v[178:179], v[134:135]
	v_pk_mul_f32 v[132:133], v[182:183], v[132:133]
	ds_write_b128 v164, v[140:143] offset:192
	ds_write_b128 v164, v[128:131] offset:12480
	ds_write_b128 v164, v[144:147] offset:4288
	global_store_dwordx4 v[176:177], v[132:135], off offset:960
	ds_write_b128 v229, v[132:135] offset:512
	s_waitcnt lgkmcnt(0)
	ds_read2st64_b32 v[128:129], v228 offset0:34 offset1:35
	v_subrev_u32_e32 v244, s94, v228
	v_and_b32_e32 v245, 0xc0, v244
	v_and_b32_e32 v244, 60, v244
	v_add_u32_e32 v244, s94, v244
	v_sub_u32_e32 v240, 0, v245
	v_ashrrev_i32_e32 v241, 31, v240
	ds_read_b32 v232, v244 offset:8704
	ds_read_b32 v233, v244 offset:8768
	ds_read_b32 v234, v244 offset:8832
	ds_read_b32 v235, v244 offset:8896
	s_waitcnt lgkmcnt(0)
	v_mov_b32_e32 v130, v129
	s_setprio 1

; #define lane LANE_()
; template <int MODE>
; __device__ __forceinline__ void scan_prologue(const ScanP& P, int m0, int seqbase, int T, int h, int d, float* slab, LAS float* lw, float* bon, int lane) {
;     const int fr = lane & 15, fq = lane >> 4, m = m0 + fr, pos = m - seqbase; const bool hp = pos > 0, hn = pos < T - 1;
;     float* srow = slab + fr * 384;
;     f32x4 k4[4], kk4[4], r4[4]; float ss = 0.f;
;     v2u pk_[4][3], pv_[4][3], pr_[4][3];
;     const int offp_ = hp ? -PRP : 0, offn_ = hn ? PRP : 0; const unsigned mp_ = hp ? 0xffffffffu : 0u, mn_ = hn ? 0xffffffffu : 0u;
; #pragma unroll
;     for (int n = 0; n < 4; ++n) { const bf16* p = P.proj + (size_t)m * PRP + h * 64 + 16 * n + 4 * fq;
;         { v2u t; pk_[n][1] = *(const v2u*)(p + 512);
;           t = *(const v2u*)(p + 512 + offp_); pk_[n][0] = (v2u){t.x & mp_, t.y & mp_};
;           t = *(const v2u*)(p + 512 + offn_); pk_[n][2] = (v2u){t.x & mn_, t.y & mn_};
;           if (MODE != 1) { pv_[n][1] = *(const v2u*)(p + 1024);
;             t = *(const v2u*)(p + 1024 + offp_); pv_[n][0] = (v2u){t.x & mp_, t.y & mp_};
;             t = *(const v2u*)(p + 1024 + offn_); pv_[n][2] = (v2u){t.x & mn_, t.y & mn_}; }
;           if (MODE == 2) { pr_[n][1] = *(const v2u*)(p);
;             t = *(const v2u*)(p + offp_); pr_[n][0] = (v2u){t.x & mp_, t.y & mp_};
;             t = *(const v2u*)(p + offn_); pr_[n][2] = (v2u){t.x & mn_, t.y & mn_}; } } }
;     v4u xw_[2]; bf16x8 xa_[2];
; #pragma unroll
;     for (int ks = 0; ks < 2; ++ks) { xw_[ks] = *(const v4u*)(P.proj + (size_t)m * PRP + 1536 + d * 64 + ks * 32 + 8 * fq); xa_[ks] = *(const bf16x8*)(P.proj + (size_t)m * PRP + 1664 + d * 64 + ks * 32 + 8 * fq); }
; template <int MODE>
; __device__ __forceinline__ void scan_item(const CAS Args* A, int l, int item, float* slab0, LAS float* ldsw, int lane) {
;     ...
;     for (int sc = 0; sc < nsub; ++sc) {
;         const int sub = d ? nsub - 1 - sc : sc, t0 = m0c + sub * 16;
;         float* slab = slab0;
;         { int lane_l = lane; asm volatile("" : "+v"(lane_l)); scan_prologue<MODE>(P, t0, seqbase, T, h, d, slab, ldsw, bon, lane_l);
.LBB0_548:
	s_setprio 0
	s_add_i32 s11, s11, 1
	s_cmp_eq_u32 s11, s3
	s_cbranch_scc1 .LBB0_546
.LBB0_549:
	s_not_b32 s4, s11
	s_add_i32 s8, s3, s4
	s_and_b64 s[4:5], s[82:83], exec
	s_cselect_b32 s4, s11, s8
	s_lshl_b32 s44, s4, 4
	v_mov_b32_e32 v184, v128
	s_add_i32 s44, s44, s47
	s_lshl_b32 s14, s53, 1
	v_and_b32_e32 v178, 15, v184
	v_or_b32_e32 v138, s44, v178
	v_subrev_u32_e32 v64, s52, v138
	v_ashrrev_i32_e32 v139, 31, v138
	v_ashrrev_i32_e32 v90, 4, v184
	v_cmp_lt_i32_e64 s[4:5], 0, v64
	v_cmp_gt_i32_e32 vcc, s46, v64
	s_waitcnt vmcnt(1)
	v_lshlrev_b64 v[64:65], 12, v[138:139]
	v_lshl_add_u64 v[80:81], s[60:61], 0, v[64:65]
	v_lshlrev_b32_e32 v64, 2, v90
	v_lshl_add_u64 v[68:69], v[80:81], 0, s[14:15]
	v_ashrrev_i32_e32 v65, 31, v64
	v_cndmask_b32_e64 v67, 0, -1, s[4:5]
	v_cndmask_b32_e64 v66, 0, v224, s[4:5]
	v_lshl_add_u64 v[86:87], v[64:65], 1, v[68:69]
	v_lshl_add_u64 v[84:85], v[86:87], 0, v[66:67]
	global_load_dwordx2 v[70:71], v[86:87], off offset:1024
	global_load_dwordx2 v[208:209], v[86:87], off offset:2048
	global_load_dwordx2 v[72:73], v[84:85], off offset:2048
	global_load_dwordx2 v[210:211], v[86:87], off
	global_load_dwordx2 v[76:77], v[84:85], off
	global_load_dwordx2 v[212:213], v[86:87], off offset:1056
	global_load_dwordx2 v[88:89], v[84:85], off offset:1056
	global_load_dwordx2 v[214:215], v[86:87], off offset:2080
	global_load_dwordx2 v[94:95], v[84:85], off offset:2080
	global_load_dwordx2 v[216:217], v[86:87], off offset:32
	global_load_dwordx2 v[100:101], v[84:85], off offset:32
	global_load_dwordx2 v[228:229], v[86:87], off offset:1088
	global_load_dwordx2 v[104:105], v[84:85], off offset:1088
	global_load_dwordx2 v[126:127], v[86:87], off offset:2112
	global_load_dwordx2 v[118:119], v[84:85], off offset:2112
	global_load_dwordx2 v[230:231], v[86:87], off offset:64
	global_load_dwordx2 v[124:125], v[84:85], off offset:64
	global_load_dwordx2 v[232:233], v[86:87], off offset:1120
	global_load_dwordx2 v[154:155], v[84:85], off offset:1120
	global_load_dwordx2 v[234:235], v[86:87], off offset:2144
	global_load_dwordx2 v[164:165], v[84:85], off offset:2144
	global_load_dwordx2 v[236:237], v[86:87], off offset:96
	global_load_dwordx2 v[200:201], v[84:85], off offset:96
	global_load_dwordx2 v[66:67], v[84:85], off offset:1024
	v_cndmask_b32_e32 v180, 0, v219, vcc
	v_lshl_add_u64 v[82:83], v[86:87], 0, v[180:181]
	global_load_dwordx2 v[68:69], v[82:83], off offset:1024
	global_load_dwordx2 v[74:75], v[82:83], off offset:2048
	global_load_dwordx2 v[78:79], v[82:83], off
	global_load_dwordx2 v[92:93], v[82:83], off offset:1056
	global_load_dwordx2 v[98:99], v[82:83], off offset:2080
	global_load_dwordx2 v[102:103], v[82:83], off offset:32
	global_load_dwordx2 v[106:107], v[82:83], off offset:1088
	global_load_dwordx2 v[120:121], v[82:83], off offset:2112
	global_load_dwordx2 v[152:153], v[82:83], off offset:64
	global_load_dwordx2 v[162:163], v[82:83], off offset:1120
	global_load_dwordx2 v[182:183], v[82:83], off offset:2144
	global_load_dwordx2 v[202:203], v[82:83], off offset:96
	s_nop 0
	v_mul_u32_u24_e32 v96, 0x180, v178
	v_lshlrev_b32_e32 v180, 2, v96
	v_lshl_add_u32 v108, v184, 4, s94
	v_lshl_add_u64 v[96:97], s[56:57], 0, v[180:181]
	v_add_u32_e32 v180, 0x2400, v108
	v_add_u32_e32 v108, s53, v64
	v_ashrrev_i32_e32 v109, 31, v108
	v_lshlrev_b64 v[150:151], 2, v[108:109]
	v_lshl_add_u64 v[110:111], s[62:63], 0, v[150:151]
	global_load_dwordx4 v[204:207], v[110:111], off offset:2048
	s_mov_b32 s85, s15
	v_lshlrev_b32_e32 v170, 3, v90
	v_lshl_add_u64 v[80:81], v[80:81], 0, s[84:85]
	v_ashrrev_i32_e32 v171, 31, v170
	v_lshl_add_u64 v[80:81], v[170:171], 1, v[80:81]
	global_load_dwordx4 v[238:241], v[80:81], off offset:3072
	global_load_dwordx4 v[242:245], v[80:81], off offset:3328
	global_load_dwordx4 v[246:249], v[80:81], off offset:3136
	v_lshlrev_b32_e32 v185, 8, v178
	s_waitcnt vmcnt(16)
	v_cndmask_b32_e64 v167, 0, v66, s[4:5]
	v_cndmask_b32_e64 v175, 0, v67, s[4:5]
	s_nop 0
	v_lshlrev_b32_e32 v186, 16, v70
	v_and_b32_e32 v187, 0xffff0000, v70
	v_lshlrev_b32_e32 v70, 16, v71
	v_and_b32_e32 v71, 0xffff0000, v71
	v_lshlrev_b32_e32 v166, 16, v167
	v_and_b32_e32 v167, 0xffff0000, v167
	v_lshlrev_b32_e32 v174, 16, v175
	v_and_b32_e32 v175, 0xffff0000, v175
	s_waitcnt vmcnt(15)
	v_cndmask_b32_e32 v188, 0, v68, vcc
	v_cndmask_b32_e32 v193, 0, v69, vcc
	s_nop 0
	s_nop 0
	v_cndmask_b32_e64 v141, 0, v72, s[4:5]
	v_cndmask_b32_e64 v140, 0, v73, s[4:5]
	s_nop 0
	s_waitcnt vmcnt(14)
	v_cndmask_b32_e32 v117, 0, v74, vcc
	v_cndmask_b32_e32 v116, 0, v75, vcc
	s_nop 0
	s_nop 0
	v_cndmask_b32_e64 v115, 0, v76, s[4:5]
	v_cndmask_b32_e64 v114, 0, v77, s[4:5]
	s_nop 0
	s_waitcnt vmcnt(13)
	v_cndmask_b32_e32 v113, 0, v78, vcc
	v_cndmask_b32_e32 v112, 0, v79, vcc
	global_load_dwordx4 v[76:79], v[110:111], off
	s_nop 0
	s_nop 0
	v_cndmask_b32_e64 v145, 0, v88, s[4:5]
	v_cndmask_b32_e64 v144, 0, v89, s[4:5]
	global_load_dwordx4 v[88:91], v[110:111], off offset:2112
	s_nop 0
	s_waitcnt vmcnt(14)
	v_cndmask_b32_e32 v143, 0, v92, vcc
	v_cndmask_b32_e32 v142, 0, v93, vcc
	s_nop 0
	s_nop 0
	v_cndmask_b32_e64 v157, 0, v94, s[4:5]
	v_cndmask_b32_e64 v156, 0, v95, s[4:5]
	s_nop 0
	s_waitcnt vmcnt(13)
	v_cndmask_b32_e32 v147, 0, v98, vcc
	v_cndmask_b32_e32 v146, 0, v99, vcc
	s_nop 0
	s_nop 0
	v_cndmask_b32_e64 v123, 0, v100, s[4:5]
	v_cndmask_b32_e64 v122, 0, v101, s[4:5]
	s_nop 0
	s_waitcnt vmcnt(12)
	v_cndmask_b32_e32 v99, 0, v102, vcc
	v_cndmask_b32_e32 v98, 0, v103, vcc
	s_nop 0
	s_nop 0
	v_cndmask_b32_e64 v160, 0, v104, s[4:5]
	v_cndmask_b32_e64 v158, 0, v105, s[4:5]
	s_nop 0
	s_waitcnt vmcnt(11)
; #define LAS __attribute__((address_space(3)))
; #define lane LANE_()
; template <int MODE>
; __device__ __forceinline__ void scan_prologue(const ScanP& P, int m0, int seqbase, int T, int h, int d, float* slab, LAS float* lw, float* bon, int lane) {
;     ...
;     const int offp_ = hp ? -PRP : 0, offn_ = hn ? PRP : 0; const unsigned mp_ = hp ? 0xffffffffu : 0u, mn_ = hn ? 0xffffffffu : 0u;
; #pragma unroll
;     for (int n = 0; n < 4; ++n) { const bf16* p = P.proj + (size_t)m * PRP + h * 64 + 16 * n + 4 * fq;
;         { v2u t; pk_[n][1] = *(const v2u*)(p + 512);
;           t = *(const v2u*)(p + 512 + offp_); pk_[n][0] = (v2u){t.x & mp_, t.y & mp_};
;           t = *(const v2u*)(p + 512 + offn_); pk_[n][2] = (v2u){t.x & mn_, t.y & mn_};
;           if (MODE != 1) { pv_[n][1] = *(const v2u*)(p + 1024);
;             t = *(const v2u*)(p + 1024 + offp_); pv_[n][0] = (v2u){t.x & mp_, t.y & mp_};
;             t = *(const v2u*)(p + 1024 + offn_); pv_[n][2] = (v2u){t.x & mn_, t.y & mn_}; }
;           if (MODE == 2) { pr_[n][1] = *(const v2u*)(p);
;             t = *(const v2u*)(p + offp_); pr_[n][0] = (v2u){t.x & mp_, t.y & mp_};
;             t = *(const v2u*)(p + offn_); pr_[n][2] = (v2u){t.x & mn_, t.y & mn_}; } } }
;     v4u xw_[2]; bf16x8 xa_[2];
; #pragma unroll
;     for (int ks = 0; ks < 2; ++ks) { xw_[ks] = *(const v4u*)(P.proj + (size_t)m * PRP + 1536 + d * 64 + ks * 32 + 8 * fq); xa_[ks] = *(const bf16x8*)(P.proj + (size_t)m * PRP + 1664 + d * 64 + ks * 32 + 8 * fq); }
;     asm volatile("" ::: "memory");
;     ...
; #pragma unroll
;     for (int n = 0; n < 4; ++n) { const int c = 16 * n + 4 * fq, col = h * 64 + c;
;         k4[n] = CONV3_(pk_, 1);
;         if (MODE != 1) { const f32x4 v4 = CONV3_(pv_, 2); *(f32x4*)(srow + 320 + c) = v4; LAS float* xsel = (fr == (d ? 15 : 0)) ? lw + 2048 + c : lw + 2304 + lane * 4; *(LAS f32x4*)(xsel + 192) = v4; }
;         if (MODE == 2) { r4[n] = CONV3_(pr_, 0); *(LAS f32x4*)(lw + 1024 + fr * 64 + c) = r4[n]; }
	v_cndmask_b32_e32 v149, 0, v106, vcc
	v_cndmask_b32_e32 v148, 0, v107, vcc
	s_nop 0
	s_nop 0
	v_cndmask_b32_e64 v159, 0, v118, s[4:5]
	v_cndmask_b32_e64 v161, 0, v119, s[4:5]
	s_nop 0
	s_waitcnt vmcnt(10)
	v_cndmask_b32_e32 v198, 0, v120, vcc
	v_cndmask_b32_e32 v189, 0, v121, vcc
	s_nop 0
	s_nop 0
	v_cndmask_b32_e64 v173, 0, v124, s[4:5]
	v_cndmask_b32_e64 v172, 0, v125, s[4:5]
	s_nop 0
	s_waitcnt vmcnt(9)
	v_cndmask_b32_e32 v169, 0, v152, vcc
	v_cndmask_b32_e32 v168, 0, v153, vcc
	s_nop 0
	s_nop 0
	v_cndmask_b32_e64 v195, 0, v154, s[4:5]
	v_cndmask_b32_e64 v194, 0, v155, s[4:5]
	s_nop 0
	s_waitcnt vmcnt(8)
	v_cndmask_b32_e32 v197, 0, v162, vcc
	v_cndmask_b32_e32 v196, 0, v163, vcc
	s_nop 0
	s_nop 0
	v_cndmask_b32_e64 v192, 0, v164, s[4:5]
	v_cndmask_b32_e64 v191, 0, v165, s[4:5]
	s_nop 0
	s_nop 0
	s_nop 0
	s_nop 0
	s_waitcnt vmcnt(7)
	v_cndmask_b32_e32 v182, 0, v182, vcc
	s_nop 0
	v_cndmask_b32_e64 v177, 0, v200, s[4:5]
	v_cndmask_b32_e64 v176, 0, v201, s[4:5]
	v_add_co_u32_e64 v124, s[4:5], s45, v110
	v_cndmask_b32_e32 v179, 0, v183, vcc
	s_nop 0
	v_addc_co_u32_e64 v125, s[4:5], 0, v111, s[4:5]
	global_load_dwordx4 v[92:95], v[124:125], off offset:64
	v_add_co_u32_e64 v108, s[4:5], s96, v110
	s_waitcnt vmcnt(7)
	v_cndmask_b32_e32 v190, 0, v202, vcc
	v_cndmask_b32_e32 v183, 0, v203, vcc
	s_nop 0
	s_nop 0
	s_nop 0
	s_nop 0
	global_load_dwordx4 v[80:83], v[80:81], off offset:3392
	v_addc_co_u32_e64 v109, s[4:5], 0, v111, s[4:5]
	global_load_dwordx4 v[152:155], v[108:109], off offset:-4096
	global_load_dwordx4 v[162:165], v[108:109], off offset:2048
	global_load_dwordx4 v[84:87], v[108:109], off
	global_load_dwordx4 v[100:103], v[108:109], off offset:2112
	s_nop 0
	s_nop 0
	s_nop 0
	v_cmp_eq_u32_e32 vcc, s48, v178
	s_waitcnt vmcnt(3)
	v_pk_mul_f32 v[70:71], v[154:155], v[70:71]
	v_pk_mul_f32 v[152:153], v[152:153], v[186:187]
	v_pk_fma_f32 v[70:71], v[206:207], v[174:175], v[70:71]
	v_pk_fma_f32 v[118:119], v[204:205], v[166:167], v[152:153]
	v_lshlrev_b32_e32 v120, 16, v188
	v_and_b32_e32 v121, 0xffff0000, v188
	v_lshl_add_u64 v[174:175], s[70:71], 0, v[150:151]
	global_load_dwordx4 v[72:75], v[174:175], off
	global_load_dwordx4 v[104:107], v[174:175], off offset:64
	s_waitcnt vmcnt(4)
	v_pk_fma_f32 v[154:155], v[162:163], v[120:121], v[118:119]
	v_add_co_u32_e64 v120, s[4:5], s26, v174
	v_lshlrev_b32_e32 v152, 16, v193
	s_nop 0
	v_addc_co_u32_e64 v121, s[4:5], 0, v175, s[4:5]
	global_load_dwordx4 v[200:203], v[120:121], off offset:2048
	v_and_b32_e32 v153, 0xffff0000, v193
	s_nop 0
	v_pk_fma_f32 v[152:153], v[164:165], v[152:153], v[70:71]
	s_nop 0
	v_add_co_u32_e64 v118, s[4:5], s96, v174
	v_lshlrev_b32_e32 v70, 16, v141
	s_nop 0
	v_addc_co_u32_e64 v119, s[4:5], 0, v175, s[4:5]
	global_load_dwordx4 v[204:207], v[118:119], off
	v_and_b32_e32 v71, 0xffff0000, v141
	v_lshlrev_b32_e32 v166, 16, v140
	v_and_b32_e32 v167, 0xffff0000, v140
	v_lshlrev_b32_e32 v140, 16, v208
	v_and_b32_e32 v141, 0xffff0000, v208
	v_lshlrev_b32_e32 v68, 16, v209
	v_and_b32_e32 v69, 0xffff0000, v209
	s_waitcnt vmcnt(1)
	v_pk_mul_f32 v[68:69], v[202:203], v[68:69]
	v_pk_mul_f32 v[140:141], v[200:201], v[140:141]
	global_load_dwordx4 v[200:203], v[120:121], off offset:2112
	v_pk_fma_f32 v[68:69], v[74:75], v[166:167], v[68:69]
	v_and_b32_e32 v166, -16, v184
	v_pk_fma_f32 v[140:141], v[72:73], v[70:71], v[140:141]
	v_lshlrev_b32_e32 v162, 16, v117
	v_and_b32_e32 v163, 0xffff0000, v117
	v_lshlrev_b32_e32 v70, 16, v116
	v_and_b32_e32 v71, 0xffff0000, v116
	v_add_u32_e32 v188, s94, v166
	s_waitcnt vmcnt(1)
	v_pk_fma_f32 v[70:71], v[206:207], v[70:71], v[68:69]
	v_pk_fma_f32 v[68:69], v[204:205], v[162:163], v[140:141]
	global_load_dwordx4 v[204:207], v[118:119], off offset:64
	v_lshl_add_u64 v[140:141], v[64:65], 2, v[96:97]
	v_add_u32_e32 v64, 0x2000, v188
	v_cndmask_b32_e32 v187, v180, v64, vcc
	v_add_co_u32_e64 v116, s[4:5], s26, v110
	global_store_dwordx4 v[140:141], v[68:71], off offset:1280
	ds_write_b128 v187, v[68:71] offset:768
	v_addc_co_u32_e64 v117, s[4:5], 0, v111, s[4:5]
	global_load_dwordx4 v[162:165], v[116:117], off offset:2048
	s_nop 0
	s_nop 0
	s_nop 0
	v_lshlrev_b32_e32 v64, 16, v115
	v_and_b32_e32 v65, 0xffff0000, v115
	v_lshlrev_b32_e32 v96, 16, v114
	v_and_b32_e32 v97, 0xffff0000, v114
	v_lshlrev_b32_e32 v114, 16, v210
	v_and_b32_e32 v115, 0xffff0000, v210
	v_lshlrev_b32_e32 v66, 16, v211
	v_and_b32_e32 v67, 0xffff0000, v211
	global_load_dwordx4 v[208:211], v[110:111], off offset:64
	v_add3_u32 v193, s94, v185, v166
	s_waitcnt vmcnt(1)
	v_pk_mul_f32 v[66:67], v[164:165], v[66:67]
	v_pk_mul_f32 v[114:115], v[162:163], v[114:115]
	v_pk_fma_f32 v[66:67], v[78:79], v[96:97], v[66:67]
	v_pk_fma_f32 v[64:65], v[76:77], v[64:65], v[114:115]
	v_lshlrev_b32_e32 v68, 16, v113
	v_and_b32_e32 v69, 0xffff0000, v113
	v_lshlrev_b32_e32 v70, 16, v112
	v_and_b32_e32 v71, 0xffff0000, v112
	v_lshl_add_u64 v[112:113], s[64:65], 0, v[150:151]
	global_load_dwordx4 v[72:75], v[112:113], off
	v_pk_fma_f32 v[70:71], v[86:87], v[70:71], v[66:67]
	v_pk_fma_f32 v[68:69], v[84:85], v[68:69], v[64:65]
	global_load_dwordx4 v[84:87], v[116:117], off offset:2112
	s_nop 0
	ds_write_b128 v193, v[68:71] offset:4096
	v_lshlrev_b32_e32 v162, 16, v144
	v_and_b32_e32 v163, 0xffff0000, v144
	v_lshlrev_b32_e32 v144, 16, v212
	s_waitcnt vmcnt(1)
; #define LAS __attribute__((address_space(3)))
; #define lane LANE_()
; template <int MODE>
; __device__ __forceinline__ void scan_prologue(const ScanP& P, int m0, int seqbase, int T, int h, int d, float* slab, LAS float* lw, float* bon, int lane) {
;     ...
; #pragma unroll
;     for (int n = 0; n < 4; ++n) { const int c = 16 * n + 4 * fq, col = h * 64 + c;
;         k4[n] = CONV3_(pk_, 1);
;         if (MODE != 1) { const f32x4 v4 = CONV3_(pv_, 2); *(f32x4*)(srow + 320 + c) = v4; LAS float* xsel = (fr == (d ? 15 : 0)) ? lw + 2048 + c : lw + 2304 + lane * 4; *(LAS f32x4*)(xsel + 192) = v4; }
;         if (MODE == 2) { r4[n] = CONV3_(pr_, 0); *(LAS f32x4*)(lw + 1024 + fr * 64 + c) = r4[n]; }
;         kk4[n] = k4[n] * *(const f32x4*)(P.k_k + col);
;         ss += (kk4[n].x * kk4[n].x + kk4[n].y * kk4[n].y) + (kk4[n].z * kk4[n].z + kk4[n].w * kk4[n].w); }
	v_pk_mul_f32 v[164:165], v[152:153], v[74:75]
	v_pk_mul_f32 v[166:167], v[154:155], v[72:73]
	v_pk_mul_f32 v[64:65], v[164:165], v[164:165]
	v_pk_mul_f32 v[66:67], v[166:167], v[166:167]
	s_nop 0
	v_pk_mov_b32 v[96:97], v[66:67], v[64:65] op_sel:[1,0]
	v_mov_b32_e32 v67, v65
	v_pk_add_f32 v[114:115], v[96:97], v[66:67]
	s_nop 0
	s_nop 0
	s_nop 0
	v_lshlrev_b32_e32 v96, 16, v145
	v_and_b32_e32 v97, 0xffff0000, v145
	v_and_b32_e32 v145, 0xffff0000, v212
	v_lshlrev_b32_e32 v78, 16, v213
	v_and_b32_e32 v79, 0xffff0000, v213
	v_pk_mul_f32 v[78:79], v[94:95], v[78:79]
	v_pk_mul_f32 v[144:145], v[92:93], v[144:145]
	global_load_dwordx4 v[92:95], v[108:109], off offset:64
	v_pk_fma_f32 v[66:67], v[90:91], v[162:163], v[78:79]
	v_pk_fma_f32 v[64:65], v[88:89], v[96:97], v[144:145]
	global_load_dwordx4 v[88:91], v[112:113], off offset:64
	v_lshlrev_b32_e32 v78, 16, v143
	v_and_b32_e32 v79, 0xffff0000, v143
	v_lshlrev_b32_e32 v96, 16, v142
	v_and_b32_e32 v97, 0xffff0000, v142
	v_pk_fma_f32 v[142:143], v[102:103], v[96:97], v[66:67]
	v_pk_fma_f32 v[144:145], v[100:101], v[78:79], v[64:65]
	global_load_dwordx4 v[100:103], v[110:111], off offset:2176
	s_nop 0
	s_nop 0
	s_nop 0
	v_lshlrev_b32_e32 v78, 16, v157
	v_and_b32_e32 v79, 0xffff0000, v157
	v_lshlrev_b32_e32 v96, 16, v156
	v_and_b32_e32 v97, 0xffff0000, v156
	v_lshlrev_b32_e32 v156, 16, v214
	v_and_b32_e32 v157, 0xffff0000, v214
	v_lshlrev_b32_e32 v74, 16, v215
	v_and_b32_e32 v75, 0xffff0000, v215
	global_load_dwordx4 v[212:215], v[124:125], off offset:128
	v_pk_mul_f32 v[74:75], v[202:203], v[74:75]
	v_pk_mul_f32 v[156:157], v[200:201], v[156:157]
	global_load_dwordx4 v[200:203], v[108:109], off offset:2176
	v_pk_fma_f32 v[66:67], v[106:107], v[96:97], v[74:75]
	v_pk_fma_f32 v[64:65], v[104:105], v[78:79], v[156:157]
	global_load_dwordx4 v[104:107], v[174:175], off offset:128
	v_lshlrev_b32_e32 v74, 16, v147
	v_and_b32_e32 v75, 0xffff0000, v147
	v_lshlrev_b32_e32 v78, 16, v146
	v_and_b32_e32 v79, 0xffff0000, v146
	v_pk_fma_f32 v[64:65], v[204:205], v[74:75], v[64:65]
	v_add_u32_e32 v74, 0x2040, v188
	v_pk_fma_f32 v[66:67], v[206:207], v[78:79], v[66:67]
	v_cndmask_b32_e32 v186, v180, v74, vcc
	global_store_dwordx4 v[140:141], v[64:67], off offset:1344
	ds_write_b128 v186, v[64:67] offset:768
	s_nop 0
	s_nop 0
	s_nop 0
	v_lshlrev_b32_e32 v96, 16, v216
	v_and_b32_e32 v97, 0xffff0000, v216
	v_lshlrev_b32_e32 v72, 16, v217
	v_and_b32_e32 v73, 0xffff0000, v217
	v_lshlrev_b32_e32 v74, 16, v123
	v_and_b32_e32 v75, 0xffff0000, v123
	v_lshlrev_b32_e32 v78, 16, v122
	v_and_b32_e32 v79, 0xffff0000, v122
	v_lshlrev_b32_e32 v146, 16, v158
	v_and_b32_e32 v147, 0xffff0000, v158
	v_lshlrev_b32_e32 v158, 16, v159
	v_and_b32_e32 v159, 0xffff0000, v159
	s_waitcnt vmcnt(7)
	v_pk_mul_f32 v[72:73], v[86:87], v[72:73]
	v_pk_mul_f32 v[96:97], v[84:85], v[96:97]
	global_load_dwordx4 v[84:87], v[120:121], off offset:2176
	v_pk_fma_f32 v[66:67], v[210:211], v[78:79], v[72:73]
	v_pk_fma_f32 v[64:65], v[208:209], v[74:75], v[96:97]
	global_load_dwordx4 v[206:209], v[118:119], off offset:128
	v_lshlrev_b32_e32 v72, 16, v99
	v_and_b32_e32 v73, 0xffff0000, v99
	v_lshlrev_b32_e32 v74, 16, v98
	v_and_b32_e32 v75, 0xffff0000, v98
	s_waitcnt vmcnt(8)
	v_pk_fma_f32 v[66:67], v[94:95], v[74:75], v[66:67]
	v_pk_fma_f32 v[64:65], v[92:93], v[72:73], v[64:65]
	global_load_dwordx4 v[92:95], v[110:111], off offset:128
	s_nop 0
	ds_write_b128 v193, v[64:67] offset:4160
	v_lshlrev_b32_e32 v204, 16, v228
	v_and_b32_e32 v205, 0xffff0000, v228
	v_lshlrev_b32_e32 v76, 16, v229
	v_and_b32_e32 v77, 0xffff0000, v229
	s_waitcnt vmcnt(8)
	v_pk_mul_f32 v[156:157], v[142:143], v[90:91]
	v_pk_mul_f32 v[162:163], v[144:145], v[88:89]
	global_load_dwordx4 v[88:91], v[116:117], off offset:2176
	v_pk_mul_f32 v[72:73], v[156:157], v[156:157]
	v_pk_mul_f32 v[74:75], v[162:163], v[162:163]
	s_nop 0
	v_pk_mov_b32 v[78:79], v[74:75], v[72:73] op_sel:[1,0]
	v_mov_b32_e32 v75, v73
	v_pk_add_f32 v[122:123], v[78:79], v[74:75]
	s_nop 0
	s_nop 0
	s_nop 0
	v_lshlrev_b32_e32 v78, 16, v160
	v_and_b32_e32 v79, 0xffff0000, v160
	v_lshlrev_b32_e32 v160, 16, v161
	v_and_b32_e32 v161, 0xffff0000, v161
	s_waitcnt vmcnt(7)
	v_pk_mul_f32 v[76:77], v[214:215], v[76:77]
	global_load_dwordx4 v[214:217], v[108:109], off offset:128
	v_pk_mul_f32 v[96:97], v[212:213], v[204:205]
	global_load_dwordx4 v[210:213], v[112:113], off offset:128
	v_pk_fma_f32 v[74:75], v[102:103], v[146:147], v[76:77]
	v_pk_fma_f32 v[72:73], v[100:101], v[78:79], v[96:97]
	v_lshlrev_b32_e32 v76, 16, v149
	v_and_b32_e32 v77, 0xffff0000, v149
	v_lshlrev_b32_e32 v78, 16, v148
	v_and_b32_e32 v79, 0xffff0000, v148
	s_waitcnt vmcnt(8)
	v_pk_fma_f32 v[146:147], v[202:203], v[78:79], v[74:75]
	global_load_dwordx4 v[202:205], v[110:111], off offset:2240
	v_pk_fma_f32 v[148:149], v[200:201], v[76:77], v[72:73]
	s_nop 0
	s_nop 0
	s_nop 0
	v_lshlrev_b32_e32 v200, 16, v126
	v_and_b32_e32 v201, 0xffff0000, v126
	v_lshlrev_b32_e32 v126, 16, v127
	v_and_b32_e32 v127, 0xffff0000, v127
	s_waitcnt vmcnt(6)
	v_pk_mul_f32 v[96:97], v[84:85], v[200:201]
	v_pk_mul_f32 v[98:99], v[86:87], v[126:127]
	global_load_dwordx4 v[84:87], v[124:125], off offset:192
	v_pk_fma_f32 v[76:77], v[104:105], v[158:159], v[96:97]
	v_lshlrev_b32_e32 v96, 16, v198
	v_and_b32_e32 v97, 0xffff0000, v198
	global_load_dwordx4 v[198:201], v[108:109], off offset:2240
	v_pk_fma_f32 v[78:79], v[106:107], v[160:161], v[98:99]
	v_lshlrev_b32_e32 v98, 16, v189
	v_and_b32_e32 v99, 0xffff0000, v189
	s_waitcnt vmcnt(7)
; #define LAS __attribute__((address_space(3)))
; __device__ __forceinline__ float shx(float v, int o, int lane) { return __builtin_bit_cast(float, __builtin_amdgcn_ds_bpermute((lane ^ o) << 2, __builtin_bit_cast(int, v))); }
; #define lane LANE_()
; template <int MODE>
; __device__ __forceinline__ void scan_prologue(const ScanP& P, int m0, int seqbase, int T, int h, int d, float* slab, LAS float* lw, float* bon, int lane) {
;     ...
; #pragma unroll
;     for (int n = 0; n < 4; ++n) { const int c = 16 * n + 4 * fq, col = h * 64 + c;
;         k4[n] = CONV3_(pk_, 1);
;         if (MODE != 1) { const f32x4 v4 = CONV3_(pv_, 2); *(f32x4*)(srow + 320 + c) = v4; LAS float* xsel = (fr == (d ? 15 : 0)) ? lw + 2048 + c : lw + 2304 + lane * 4; *(LAS f32x4*)(xsel + 192) = v4; }
;         if (MODE == 2) { r4[n] = CONV3_(pr_, 0); *(LAS f32x4*)(lw + 1024 + fr * 64 + c) = r4[n]; }
;         kk4[n] = k4[n] * *(const f32x4*)(P.k_k + col);
;         ss += (kk4[n].x * kk4[n].x + kk4[n].y * kk4[n].y) + (kk4[n].z * kk4[n].z + kk4[n].w * kk4[n].w); }
;     ...
;     ss += shx(ss, 16, lane); ss += shx(ss, 32, lane);
;     ...
;         for (int n = 0; n < 4; ++n) { const size_t wo = (size_t)(h * 64 + 16 * n + fr) * 64 + ks * 32 + 8 * fq;
;             Dw[n] = __builtin_amdgcn_mfma_f32_16x16x32_bf16(*(const bf16x8*)(P.upw + wo), twv, Dw[n], 0, 0, 0);
;             Da[n] = __builtin_amdgcn_mfma_f32_16x16x32_bf16(*(const bf16x8*)(P.upa + wo), xa, Da[n], 0, 0, 0); }
	v_pk_fma_f32 v[72:73], v[206:207], v[96:97], v[76:77]
	v_add_u32_e32 v76, 0x2080, v188
	v_pk_fma_f32 v[74:75], v[208:209], v[98:99], v[78:79]
	global_load_dwordx4 v[206:209], v[174:175], off offset:192
	v_cndmask_b32_e32 v189, v180, v76, vcc
	global_store_dwordx4 v[140:141], v[72:75], off offset:1408
	ds_write_b128 v189, v[72:75] offset:768
	s_nop 0
	s_nop 0
	s_nop 0
	v_lshlrev_b32_e32 v160, 16, v230
	v_and_b32_e32 v161, 0xffff0000, v230
	v_lshlrev_b32_e32 v100, 16, v231
	v_and_b32_e32 v101, 0xffff0000, v231
	global_load_dwordx4 v[228:231], v[120:121], off offset:2240
	v_lshlrev_b32_e32 v126, 16, v173
	v_and_b32_e32 v127, 0xffff0000, v173
	v_lshlrev_b32_e32 v158, 16, v172
	v_and_b32_e32 v159, 0xffff0000, v172
	s_waitcnt vmcnt(8)
	v_pk_mul_f32 v[78:79], v[90:91], v[100:101]
	v_pk_mul_f32 v[76:77], v[88:89], v[160:161]
	global_load_dwordx4 v[88:91], v[118:119], off offset:192
	v_pk_fma_f32 v[74:75], v[94:95], v[158:159], v[78:79]
	v_pk_fma_f32 v[72:73], v[92:93], v[126:127], v[76:77]
	global_load_dwordx4 v[92:95], v[110:111], off offset:192
	v_lshlrev_b32_e32 v76, 16, v169
	v_and_b32_e32 v77, 0xffff0000, v169
	v_lshlrev_b32_e32 v78, 16, v168
	v_and_b32_e32 v79, 0xffff0000, v168
	s_waitcnt vmcnt(9)
	v_pk_fma_f32 v[78:79], v[216:217], v[78:79], v[74:75]
	v_pk_fma_f32 v[76:77], v[214:215], v[76:77], v[72:73]
	global_load_dwordx4 v[214:217], v[116:117], off offset:2240
	s_nop 0
	ds_write_b128 v193, v[76:79] offset:4224
	v_lshlrev_b32_e32 v160, 16, v232
	v_and_b32_e32 v161, 0xffff0000, v232
	v_lshlrev_b32_e32 v102, 16, v233
	v_and_b32_e32 v103, 0xffff0000, v233
	v_lshlrev_b32_e32 v100, 16, v195
	v_and_b32_e32 v101, 0xffff0000, v195
	v_lshlrev_b32_e32 v158, 16, v194
	v_and_b32_e32 v159, 0xffff0000, v194
	s_waitcnt vmcnt(9)
	v_pk_mul_f32 v[168:169], v[146:147], v[212:213]
	v_pk_mul_f32 v[172:173], v[148:149], v[210:211]
	global_load_dwordx4 v[210:213], v[108:109], off offset:192
	s_nop 0
	s_nop 0
	s_nop 0
	s_nop 0
	s_waitcnt vmcnt(8)
	v_pk_mul_f32 v[98:99], v[86:87], v[102:103]
	v_pk_mul_f32 v[96:97], v[84:85], v[160:161]
	global_load_dwordx4 v[84:87], v[112:113], off offset:192
	v_pk_fma_f32 v[74:75], v[204:205], v[158:159], v[98:99]
	v_pk_fma_f32 v[72:73], v[202:203], v[100:101], v[96:97]
	v_lshlrev_b32_e32 v96, 16, v197
	v_and_b32_e32 v97, 0xffff0000, v197
	v_lshlrev_b32_e32 v98, 16, v196
	v_and_b32_e32 v99, 0xffff0000, v196
	s_waitcnt vmcnt(8)
	v_pk_fma_f32 v[158:159], v[200:201], v[98:99], v[74:75]
	v_pk_fma_f32 v[160:161], v[198:199], v[96:97], v[72:73]
	s_nop 0
	s_nop 0
	s_nop 0
	v_lshlrev_b32_e32 v124, 16, v234
	v_and_b32_e32 v125, 0xffff0000, v234
	v_lshlrev_b32_e32 v118, 16, v192
	v_and_b32_e32 v119, 0xffff0000, v192
	v_lshlrev_b32_e32 v106, 16, v235
	v_and_b32_e32 v107, 0xffff0000, v235
	v_lshlrev_b32_e32 v120, 16, v191
	v_and_b32_e32 v121, 0xffff0000, v191
	s_waitcnt vmcnt(5)
	v_pk_mul_f32 v[96:97], v[228:229], v[124:125]
	v_pk_mul_f32 v[98:99], v[230:231], v[106:107]
	v_pk_fma_f32 v[72:73], v[206:207], v[118:119], v[96:97]
	v_lshlrev_b32_e32 v96, 16, v182
	v_and_b32_e32 v97, 0xffff0000, v182
	v_pk_fma_f32 v[74:75], v[208:209], v[120:121], v[98:99]
	v_lshlrev_b32_e32 v98, 16, v179
	v_and_b32_e32 v99, 0xffff0000, v179
	s_waitcnt vmcnt(4)
	v_pk_fma_f32 v[72:73], v[88:89], v[96:97], v[72:73]
	v_add_u32_e32 v96, 0x20c0, v188
	v_pk_fma_f32 v[74:75], v[90:91], v[98:99], v[74:75]
	v_cndmask_b32_e32 v192, v180, v96, vcc
	global_store_dwordx4 v[140:141], v[72:75], off offset:1472
	ds_write_b128 v192, v[72:75] offset:768
	s_nop 0
	s_nop 0
	s_nop 0
	v_lshlrev_b32_e32 v110, 16, v236
	v_and_b32_e32 v111, 0xffff0000, v236
	v_lshlrev_b32_e32 v104, 16, v237
	v_and_b32_e32 v105, 0xffff0000, v237
	v_lshlrev_b32_e32 v106, 16, v177
	v_and_b32_e32 v107, 0xffff0000, v177
	v_lshlrev_b32_e32 v108, 16, v176
	v_and_b32_e32 v109, 0xffff0000, v176
	v_lshl_or_b32 v180, v178, 6, s49
	v_or_b32_e32 v120, 0xc00, v180
	v_mov_b32_e32 v121, v181
	v_lshl_add_u64 v[120:121], v[120:121], 0, v[170:171]
	v_lshlrev_b64 v[124:125], 1, v[120:121]
	v_lshl_add_u64 v[120:121], s[76:77], 0, v[124:125]
	global_load_dwordx4 v[194:197], v[120:121], off
	v_cmp_gt_u32_e32 vcc, 16, v184
	s_waitcnt vmcnt(4)
	v_pk_mul_f32 v[98:99], v[216:217], v[104:105]
	v_pk_mul_f32 v[96:97], v[214:215], v[110:111]
	v_pk_fma_f32 v[74:75], v[94:95], v[108:109], v[98:99]
	v_pk_fma_f32 v[72:73], v[92:93], v[106:107], v[96:97]
	v_lshlrev_b32_e32 v96, 16, v190
	v_and_b32_e32 v97, 0xffff0000, v190
	v_lshlrev_b32_e32 v98, 16, v183
	v_and_b32_e32 v99, 0xffff0000, v183
	s_waitcnt vmcnt(3)
	v_pk_fma_f32 v[74:75], v[212:213], v[98:99], v[74:75]
	v_pk_fma_f32 v[72:73], v[210:211], v[96:97], v[72:73]
	s_nop 0
	ds_write_b128 v193, v[72:75] offset:4288
	v_or_b32_e32 v112, 0x800, v180
	v_mov_b32_e32 v113, v181
	v_lshl_add_u64 v[112:113], v[112:113], 0, v[170:171]
	v_lshlrev_b64 v[116:117], 1, v[112:113]
	v_lshl_add_u64 v[112:113], s[76:77], 0, v[116:117]
	global_load_dwordx4 v[88:91], v[112:113], off
	v_lshl_add_u64 v[116:117], s[78:79], 0, v[116:117]
	global_load_dwordx4 v[116:119], v[116:117], off
	s_waitcnt vmcnt(4)
	v_pk_mul_f32 v[176:177], v[160:161], v[84:85]
	v_pk_mul_f32 v[174:175], v[158:159], v[86:87]
	v_mul_f32_e32 v98, v176, v176
	v_pk_add_f32 v[96:97], v[114:115], v[114:115] op_sel:[0,1] op_sel_hi:[1,0]
	v_mul_f32_e32 v100, v177, v177
	v_mov_b32_e32 v97, v98
	v_pk_add_f32 v[98:99], v[122:123], v[122:123] op_sel:[0,1] op_sel_hi:[1,0]
	v_mul_f32_e32 v101, v174, v174
	v_mov_b32_e32 v99, v100
	v_pk_add_f32 v[96:97], v[96:97], v[98:99]
	v_mul_f32_e32 v98, v173, v173
	v_pk_fma_f32 v[98:99], v[172:173], v[172:173], v[98:99] op_sel_hi:[1,1,0]
	v_mul_f32_e32 v100, v169, v169
	v_mul_f32_e32 v102, v175, v175
	v_mov_b32_e32 v99, v101
	v_pk_fma_f32 v[100:101], v[168:169], v[168:169], v[100:101] op_sel_hi:[1,1,0]
	s_nop 0
	v_mov_b32_e32 v101, v102
	v_pk_add_f32 v[98:99], v[98:99], v[100:101]
	s_nop 0
	v_pk_add_f32 v[96:97], v[96:97], v[98:99]
	s_nop 0
	v_add_f32_e32 v96, v96, v97
	v_lshlrev_b32_e32 v97, 2, v184
	v_xor_b32_e32 v191, 64, v97
	ds_bpermute_b32 v98, v191, v96
	v_xor_b32_e32 v190, 0x80, v97
	s_waitcnt lgkmcnt(0)
; __device__ __forceinline__ unsigned pk2(float lo, float hi) { const f2 v = {lo, hi}; return __builtin_bit_cast(unsigned, __builtin_convertvector(v, bf16x2_hw)); }
; __device__ __forceinline__ float tanhf_(float x) { return 1.0f - 2.0f * __builtin_amdgcn_rcpf(1.0f + __builtin_amdgcn_exp2f(2.8853900817779268f * x)); }
; template <int MODE>
; __device__ __forceinline__ void scan_prologue(const ScanP& P, int m0, int seqbase, int T, int h, int d, float* slab, LAS float* lw, float* bon, int lane) {
;     ...
; #pragma unroll
;     for (int ks = 0; ks < 2; ++ks) {
;         const v4u xw = xw_[ks]; const bf16x8 xa = xa_[ks];
;         v4u tw;
; #pragma unroll
;         for (int e = 0; e < 4; ++e) tw[e] = pk2(tanhf_(bflo(xw[e])), tanhf_(bfhi(xw[e])));
;         const bf16x8 twv = __builtin_bit_cast(bf16x8, tw);
; #pragma unroll
;         for (int n = 0; n < 4; ++n) { const size_t wo = (size_t)(h * 64 + 16 * n + fr) * 64 + ks * 32 + 8 * fq;
;             Dw[n] = __builtin_amdgcn_mfma_f32_16x16x32_bf16(*(const bf16x8*)(P.upw + wo), twv, Dw[n], 0, 0, 0);
;             Da[n] = __builtin_amdgcn_mfma_f32_16x16x32_bf16(*(const bf16x8*)(P.upa + wo), xa, Da[n], 0, 0, 0); }
;     }
;     float bp = 0.f;
; #pragma unroll
;     for (int n = 0; n < 4; ++n) { const int c = 16 * n + 4 * fq, col = h * 64 + c;
;         const f32x4 w0 = *(const f32x4*)(P.w0 + col), a0 = *(const f32x4*)(P.a0 + col), ka = *(const f32x4*)(P.k_a + col);
	v_add_f32_e32 v96, v96, v98
	ds_bpermute_b32 v97, v190, v96
	s_waitcnt lgkmcnt(0)
	v_add_f32_e32 v96, v96, v97
	v_add_f32_e32 v193, 0x2b8cbccc, v96
	v_lshlrev_b32_e32 v96, 16, v238
	v_and_b32_e32 v92, 0xffff0000, v238
	v_mul_f32_e32 v92, 0x4038aa3b, v92
	v_exp_f32_e32 v92, v92
	v_mul_f32_e32 v96, 0x4038aa3b, v96
	v_exp_f32_e32 v96, v96
	v_add_f32_e32 v92, 1.0, v92
	v_rcp_f32_e32 v97, v92
	v_lshlrev_b32_e32 v92, 16, v239
	v_and_b32_e32 v93, 0xffff0000, v239
	v_mul_f32_e32 v92, 0x4038aa3b, v92
	v_mul_f32_e32 v93, 0x4038aa3b, v93
	v_exp_f32_e32 v92, v92
	v_exp_f32_e32 v93, v93
	v_add_f32_e32 v96, 1.0, v96
	v_rcp_f32_e32 v96, v96
	v_add_f32_e32 v92, 1.0, v92
	v_add_f32_e32 v93, 1.0, v93
	v_rcp_f32_e32 v92, v92
	v_rcp_f32_e32 v93, v93
	v_pk_fma_f32 v[96:97], v[96:97], 2.0, 1.0 op_sel_hi:[1,0,0] neg_lo:[1,0,0] neg_hi:[1,0,0]
	v_pk_fma_f32 v[92:93], v[92:93], 2.0, 1.0 op_sel_hi:[1,0,0] neg_lo:[1,0,0] neg_hi:[1,0,0]
	s_nop 0
	v_cvt_pk_bf16_f32 v105, v92, v93
	v_lshlrev_b32_e32 v92, 16, v240
	v_and_b32_e32 v93, 0xffff0000, v240
	v_mul_f32_e32 v92, 0x4038aa3b, v92
	v_mul_f32_e32 v93, 0x4038aa3b, v93
	v_exp_f32_e32 v92, v92
	v_exp_f32_e32 v93, v93
	v_cvt_pk_bf16_f32 v104, v96, v97
	v_add_f32_e32 v92, 1.0, v92
	v_add_f32_e32 v93, 1.0, v93
	v_rcp_f32_e32 v92, v92
	v_rcp_f32_e32 v93, v93
	s_nop 0
	v_pk_fma_f32 v[92:93], v[92:93], 2.0, 1.0 op_sel_hi:[1,0,0] neg_lo:[1,0,0] neg_hi:[1,0,0]
	s_nop 0
	v_cvt_pk_bf16_f32 v106, v92, v93
	v_lshlrev_b32_e32 v92, 16, v241
	v_and_b32_e32 v93, 0xffff0000, v241
	v_mul_f32_e32 v92, 0x4038aa3b, v92
	v_mul_f32_e32 v93, 0x4038aa3b, v93
	v_exp_f32_e32 v92, v92
	v_exp_f32_e32 v93, v93
	v_add_f32_e32 v92, 1.0, v92
	v_add_f32_e32 v93, 1.0, v93
	v_rcp_f32_e32 v92, v92
	v_rcp_f32_e32 v93, v93
	s_nop 0
	v_pk_fma_f32 v[92:93], v[92:93], 2.0, 1.0 op_sel_hi:[1,0,0] neg_lo:[1,0,0] neg_hi:[1,0,0]
	s_nop 0
	v_cvt_pk_bf16_f32 v107, v92, v93
	v_lshl_add_u64 v[92:93], v[180:181], 0, v[170:171]
	v_lshlrev_b64 v[96:97], 1, v[92:93]
	v_lshl_add_u64 v[178:179], s[76:77], 0, v[96:97]
	global_load_dwordx4 v[84:87], v[178:179], off offset:2048
	global_load_dwordx4 v[202:205], v[178:179], off offset:64
	global_load_dwordx4 v[210:213], v[178:179], off offset:2112
	global_load_dwordx4 v[92:95], v[178:179], off
	v_lshl_add_u64 v[182:183], s[78:79], 0, v[96:97]
	global_load_dwordx4 v[198:201], v[182:183], off
	global_load_dwordx4 v[100:103], v[182:183], off offset:2048
	global_load_dwordx4 v[206:209], v[182:183], off offset:64
	global_load_dwordx4 v[214:217], v[182:183], off offset:2112
	s_nop 0
	s_waitcnt vmcnt(4)
	v_mfma_f32_16x16x32_bf16 v[108:111], v[92:95], v[104:107], 0
	s_nop 0
	s_nop 0
	v_mfma_f32_16x16x32_bf16 v[96:99], v[84:87], v[104:107], 0
	v_mfma_f32_16x16x32_bf16 v[112:115], v[88:91], v[104:107], 0
	v_mfma_f32_16x16x32_bf16 v[120:123], v[194:197], v[104:107], 0
	v_lshl_add_u64 v[104:105], s[78:79], 0, v[124:125]
	global_load_dwordx4 v[104:107], v[104:105], off
	s_waitcnt vmcnt(4)
	v_mfma_f32_16x16x32_bf16 v[92:95], v[198:201], v[242:245], 0
	s_waitcnt vmcnt(3)
	v_mfma_f32_16x16x32_bf16 v[100:103], v[100:103], v[242:245], 0
	v_mfma_f32_16x16x32_bf16 v[116:119], v[116:119], v[242:245], 0
	s_waitcnt vmcnt(0)
	v_mfma_f32_16x16x32_bf16 v[124:127], v[104:107], v[242:245], 0
	v_lshlrev_b32_e32 v88, 16, v246
	v_and_b32_e32 v84, 0xffff0000, v246
	v_mul_f32_e32 v88, 0x4038aa3b, v88
	v_mul_f32_e32 v84, 0x4038aa3b, v84
	v_exp_f32_e32 v88, v88
	v_exp_f32_e32 v84, v84
	v_add_f32_e32 v88, 1.0, v88
	v_add_f32_e32 v84, 1.0, v84
	v_rcp_f32_e32 v88, v88
	v_rcp_f32_e32 v89, v84
	s_nop 0
	v_pk_fma_f32 v[88:89], v[88:89], 2.0, 1.0 op_sel_hi:[1,0,0] neg_lo:[1,0,0] neg_hi:[1,0,0]
	s_nop 0
	v_cvt_pk_bf16_f32 v84, v88, v89
	v_lshlrev_b32_e32 v88, 16, v247
	v_and_b32_e32 v85, 0xffff0000, v247
	v_mul_f32_e32 v88, 0x4038aa3b, v88
	v_mul_f32_e32 v85, 0x4038aa3b, v85
	v_exp_f32_e32 v88, v88
	v_exp_f32_e32 v85, v85
	v_add_f32_e32 v88, 1.0, v88
	v_add_f32_e32 v85, 1.0, v85
	v_rcp_f32_e32 v88, v88
	v_rcp_f32_e32 v89, v85
	s_nop 0
	v_pk_fma_f32 v[88:89], v[88:89], 2.0, 1.0 op_sel_hi:[1,0,0] neg_lo:[1,0,0] neg_hi:[1,0,0]
	s_nop 0
	v_cvt_pk_bf16_f32 v85, v88, v89
	v_lshlrev_b32_e32 v88, 16, v248
	v_and_b32_e32 v86, 0xffff0000, v248
	v_mul_f32_e32 v88, 0x4038aa3b, v88
	v_mul_f32_e32 v86, 0x4038aa3b, v86
	v_exp_f32_e32 v88, v88
	v_exp_f32_e32 v86, v86
	v_add_f32_e32 v88, 1.0, v88
	v_add_f32_e32 v86, 1.0, v86
	v_rcp_f32_e32 v88, v88
	v_rcp_f32_e32 v89, v86
	s_nop 0
	v_pk_fma_f32 v[88:89], v[88:89], 2.0, 1.0 op_sel_hi:[1,0,0] neg_lo:[1,0,0] neg_hi:[1,0,0]
	s_nop 0
	v_cvt_pk_bf16_f32 v86, v88, v89
	v_lshlrev_b32_e32 v88, 16, v249
	v_and_b32_e32 v87, 0xffff0000, v249
	v_mul_f32_e32 v88, 0x4038aa3b, v88
	v_mul_f32_e32 v87, 0x4038aa3b, v87
	v_exp_f32_e32 v88, v88
	v_exp_f32_e32 v87, v87
	v_add_f32_e32 v88, 1.0, v88
	v_add_f32_e32 v87, 1.0, v87
	v_rcp_f32_e32 v88, v88
	v_rcp_f32_e32 v89, v87
	s_nop 0
	v_pk_fma_f32 v[88:89], v[88:89], 2.0, 1.0 op_sel_hi:[1,0,0] neg_lo:[1,0,0] neg_hi:[1,0,0]
	s_nop 0
	v_cvt_pk_bf16_f32 v87, v88, v89
	s_nop 0
	v_mfma_f32_16x16x32_bf16 v[104:107], v[202:205], v[84:87], v[108:111]
	s_nop 0
	v_mfma_f32_16x16x32_bf16 v[108:111], v[206:209], v[80:83], v[92:95]
	s_nop 0
	v_lshl_add_u64 v[178:179], s[66:67], 0, v[150:151]
	global_load_dwordx4 v[198:201], v[178:179], off
	global_load_dwordx4 v[202:205], v[178:179], off offset:64
	global_load_dwordx4 v[232:235], v[178:179], off offset:128
	global_load_dwordx4 v[236:239], v[178:179], off offset:192
	v_mfma_f32_16x16x32_bf16 v[96:99], v[210:213], v[84:87], v[96:99]
	s_nop 0
	v_mfma_f32_16x16x32_bf16 v[100:103], v[214:217], v[80:83], v[100:103]
	v_or_b32_e32 v88, 0x820, v180
	v_mov_b32_e32 v89, v181
	v_lshl_add_u64 v[88:89], v[88:89], 0, v[170:171]
	v_lshlrev_b64 v[92:93], 1, v[88:89]
	v_lshl_add_u64 v[88:89], s[76:77], 0, v[92:93]
	global_load_dwordx4 v[88:91], v[88:89], off
	v_lshl_add_u64 v[92:93], s[78:79], 0, v[92:93]
	global_load_dwordx4 v[92:95], v[92:93], off
	v_or_b32_e32 v180, 0xc20, v180
	s_waitcnt vmcnt(1)
; #define LAS __attribute__((address_space(3)))
; __device__ __forceinline__ float sigmoidf_(float x) { return __builtin_amdgcn_rcpf(1.0f + __builtin_amdgcn_exp2f(-1.4426950408889634f * x)); }
; #define lane LANE_()
; template <int MODE>
; __device__ __forceinline__ void scan_prologue(const ScanP& P, int m0, int seqbase, int T, int h, int d, float* slab, LAS float* lw, float* bon, int lane) {
;     ...
;     for (int n = 0; n < 4; ++n) { const int c = 16 * n + 4 * fq, col = h * 64 + c;
;         const f32x4 w0 = *(const f32x4*)(P.w0 + col), a0 = *(const f32x4*)(P.a0 + col), ka = *(const f32x4*)(P.k_a + col);
;         f32x4 wv, bv, kd, av;
; #pragma unroll
;         for (int i = 0; i < 4; ++i) { const float ic = sigmoidf_(Da[n][i] + a0[i]);
;             wv[i] = __builtin_amdgcn_exp2f(-DECAY_SCALE * 1.4426950408889634f * sigmoidf_(Dw[n][i] + w0[i]));
;             const float kk = kk4[n][i] * rs; av[i] = -kk; bv[i] = kk * ic; kd[i] = k4[n][i] * (1.0f + (ic - 1.0f) * ka[i]); }
;         *(LAS f32x4*)(lw + fr * 64 + c) = av; *(LAS f32x4*)(lw + 3072 + fr * 64 + c) = wv; *(LAS f32x4*)(lw + (MODE == 3 ? 1024 : 4096) + fr * 64 + c) = bv;
;         if (MODE != 1) *(f32x4*)(srow + 192 + c) = kd;
;         { LAS float* xsel = (fr == (d ? 15 : 0)) ? lw + 2048 + c : lw + 2304 + lane * 4;
;           if (MODE != 1) *(LAS f32x4*)(xsel + 128) = kd; }
;         if (MODE == 2) { const f32x4 rk = *(const f32x4*)(P.r_k + col); const f32x4 t = r4[n] * kd * rk; bp += (t.x + t.y) + (t.z + t.w); }
	v_mfma_f32_16x16x32_bf16 v[88:91], v[88:91], v[84:87], v[112:115]
	s_nop 2
	v_lshl_add_u64 v[112:113], v[180:181], 0, v[170:171]
	v_lshl_add_u64 v[170:171], s[74:75], 0, v[150:151]
	global_load_dwordx4 v[194:197], v[170:171], off
	global_load_dwordx4 v[206:209], v[170:171], off offset:64
	global_load_dwordx4 v[228:231], v[170:171], off offset:128
	global_load_dwordx4 v[240:243], v[170:171], off offset:192
	s_waitcnt vmcnt(4)
	v_mfma_f32_16x16x32_bf16 v[92:95], v[92:95], v[80:83], v[116:119]
	s_nop 2
	v_lshlrev_b64 v[116:117], 1, v[112:113]
	v_lshl_add_u64 v[112:113], s[76:77], 0, v[116:117]
	global_load_dwordx4 v[112:115], v[112:113], off
	s_waitcnt vmcnt(0)
	v_mfma_f32_16x16x32_bf16 v[84:87], v[112:115], v[84:87], v[120:123]
	v_lshl_add_u64 v[112:113], s[78:79], 0, v[116:117]
	global_load_dwordx4 v[112:115], v[112:113], off
	s_nop 0
	s_nop 0
	s_waitcnt vmcnt(0)
	v_mfma_f32_16x16x32_bf16 v[80:83], v[112:115], v[80:83], v[124:127]
	s_nop 2
	v_lshl_add_u64 v[126:127], s[72:73], 0, v[150:151]
	global_load_dwordx4 v[210:213], v[126:127], off offset:64
	global_load_dwordx4 v[214:217], v[126:127], off offset:128
	global_load_dwordx4 v[244:247], v[126:127], off offset:192
	global_load_dwordx4 v[112:115], v[126:127], off
	s_nop 0
	v_add_f32_e32 v108, v108, v194
	v_add_f32_e32 v110, v110, v196
	v_mul_f32_e32 v108, 0xbfb8aa3b, v108
	v_mul_f32_e32 v110, 0xbfb8aa3b, v110
	v_exp_f32_e32 v108, v108
	v_exp_f32_e32 v110, v110
	v_rsq_f32_e32 v124, v193
	v_add_f32_e32 v108, 1.0, v108
	v_add_f32_e32 v110, 1.0, v110
	v_rcp_f32_e32 v182, v108
	v_add_f32_e32 v108, v109, v195
	v_mul_f32_e32 v108, 0xbfb8aa3b, v108
	v_exp_f32_e32 v108, v108
	s_waitcnt vmcnt(0)
	v_add_f32_e32 v104, v104, v112
	v_add_f32_e32 v105, v105, v113
	v_add_f32_e32 v106, v106, v114
	v_add_f32_e32 v107, v107, v115
	v_mul_f32_e32 v104, 0xbfb8aa3b, v104
	v_mul_f32_e32 v105, 0xbfb8aa3b, v105
	v_pk_mul_f32 v[112:113], v[166:167], v[124:125] op_sel_hi:[1,0]
	v_rcp_f32_e32 v166, v110
	v_mul_f32_e32 v106, 0xbfb8aa3b, v106
	v_add_f32_e32 v110, v111, v197
	v_mul_f32_e32 v107, 0xbfb8aa3b, v107
	v_exp_f32_e32 v104, v104
	v_exp_f32_e32 v105, v105
	v_exp_f32_e32 v106, v106
	v_mul_f32_e32 v110, 0xbfb8aa3b, v110
	v_exp_f32_e32 v107, v107
	v_exp_f32_e32 v110, v110
	v_add_f32_e32 v104, 1.0, v104
	v_add_f32_e32 v105, 1.0, v105
	v_add_f32_e32 v106, 1.0, v106
	v_add_f32_e32 v107, 1.0, v107
	v_rcp_f32_e32 v104, v104
	v_add_f32_e32 v108, 1.0, v108
	v_rcp_f32_e32 v105, v105
	v_rcp_f32_e32 v106, v106
	v_add_f32_e32 v110, 1.0, v110
	v_rcp_f32_e32 v107, v107
	v_rcp_f32_e32 v183, v108
	v_rcp_f32_e32 v167, v110
	v_mul_f32_e32 v104, 0xbf60028a, v104
	v_mul_f32_e32 v105, 0xbf60028a, v105
	v_mul_f32_e32 v106, 0xbf60028a, v106
	v_mul_f32_e32 v107, 0xbf60028a, v107
	v_pk_mul_f32 v[114:115], v[164:165], v[124:125] op_sel_hi:[1,0]
	v_exp_f32_e32 v104, v104
	v_exp_f32_e32 v105, v105
	v_xor_b32_e32 v109, 0x80000000, v113
	v_xor_b32_e32 v108, 0x80000000, v112
	v_exp_f32_e32 v106, v106
	v_exp_f32_e32 v107, v107
	v_xor_b32_e32 v110, 0x80000000, v114
	v_xor_b32_e32 v111, 0x80000000, v115
	v_pk_mul_f32 v[116:117], v[112:113], v[182:183]
	v_pk_mul_f32 v[118:119], v[114:115], v[166:167]
	v_pk_add_f32 v[112:113], v[166:167], -1.0 op_sel_hi:[1,0]
	v_pk_add_f32 v[114:115], v[182:183], -1.0 op_sel_hi:[1,0]
	v_pk_fma_f32 v[112:113], v[200:201], v[112:113], 1.0 op_sel_hi:[1,1,0]
	v_pk_fma_f32 v[114:115], v[198:199], v[114:115], 1.0 op_sel_hi:[1,1,0]
	v_pk_mul_f32 v[122:123], v[152:153], v[112:113]
	v_pk_mul_f32 v[120:121], v[154:155], v[114:115]
	v_add_u32_e32 v114, v188, v185
	ds_write_b128 v114, v[108:111]
	ds_write_b128 v114, v[104:107] offset:12288
	ds_write_b128 v114, v[116:119] offset:16384
	global_store_dwordx4 v[140:141], v[120:123], off offset:768
	v_lshl_add_u64 v[112:113], s[68:69], 0, v[150:151]
	global_load_dwordx4 v[116:119], v[112:113], off offset:64
	global_load_dwordx4 v[150:153], v[112:113], off offset:128
	global_load_dwordx4 v[164:167], v[112:113], off offset:192
	global_load_dwordx4 v[104:107], v[112:113], off
	v_pk_mul_f32 v[70:71], v[70:71], v[122:123]
	v_pk_mul_f32 v[68:69], v[68:69], v[120:121]
	ds_write_b128 v187, v[120:123] offset:512
	s_waitcnt vmcnt(0)
	v_pk_mul_f32 v[70:71], v[106:107], v[70:71]
	v_pk_mul_f32 v[68:69], v[104:105], v[68:69]
	s_nop 0
	v_add_f32_e32 v68, v68, v69
	v_add_f32_e32 v69, v70, v71
	v_add_f32_e32 v68, v68, v69
	v_add_f32_e32 v115, 0, v68
	s_nop 0
	s_nop 0
	s_nop 0
	v_add_f32_e32 v100, v100, v206
	v_add_f32_e32 v96, v96, v210
	v_add_f32_e32 v97, v97, v211
	v_add_f32_e32 v98, v98, v212
	v_add_f32_e32 v99, v99, v213
	v_mul_f32_e32 v96, 0xbfb8aa3b, v96
	v_add_f32_e32 v101, v101, v207
	v_mul_f32_e32 v97, 0xbfb8aa3b, v97
	v_add_f32_e32 v102, v102, v208
	v_mul_f32_e32 v98, 0xbfb8aa3b, v98
	v_add_f32_e32 v103, v103, v209
	v_mul_f32_e32 v99, 0xbfb8aa3b, v99
	v_mul_f32_e32 v100, 0xbfb8aa3b, v100
	v_exp_f32_e32 v96, v96
	v_mul_f32_e32 v101, 0xbfb8aa3b, v101
	v_exp_f32_e32 v97, v97
	v_mul_f32_e32 v102, 0xbfb8aa3b, v102
	v_exp_f32_e32 v98, v98
	v_mul_f32_e32 v103, 0xbfb8aa3b, v103
	v_exp_f32_e32 v99, v99
	v_exp_f32_e32 v100, v100
	v_exp_f32_e32 v101, v101
	v_exp_f32_e32 v102, v102
	v_exp_f32_e32 v103, v103
	v_add_f32_e32 v96, 1.0, v96
	v_add_f32_e32 v97, 1.0, v97
	v_add_f32_e32 v98, 1.0, v98
	v_add_f32_e32 v99, 1.0, v99
	v_add_f32_e32 v100, 1.0, v100
	v_rcp_f32_e32 v96, v96
	v_add_f32_e32 v101, 1.0, v101
	v_rcp_f32_e32 v97, v97
	v_add_f32_e32 v102, 1.0, v102
	v_rcp_f32_e32 v98, v98
	v_add_f32_e32 v103, 1.0, v103
	v_rcp_f32_e32 v99, v99
	v_rcp_f32_e32 v100, v100
	v_rcp_f32_e32 v101, v101
	v_rcp_f32_e32 v102, v102
	v_rcp_f32_e32 v103, v103
	v_mul_f32_e32 v96, 0xbf60028a, v96
	v_mul_f32_e32 v97, 0xbf60028a, v97
; #define LAS __attribute__((address_space(3)))
; __device__ __forceinline__ float sigmoidf_(float x) { return __builtin_amdgcn_rcpf(1.0f + __builtin_amdgcn_exp2f(-1.4426950408889634f * x)); }
; __device__ __forceinline__ float shx(float v, int o, int lane) { return __builtin_bit_cast(float, __builtin_amdgcn_ds_bpermute((lane ^ o) << 2, __builtin_bit_cast(int, v))); }
; #define lane LANE_()
; template <int MODE>
; __device__ __forceinline__ void scan_prologue(const ScanP& P, int m0, int seqbase, int T, int h, int d, float* slab, LAS float* lw, float* bon, int lane) {
;     ...
;     for (int n = 0; n < 4; ++n) { const int c = 16 * n + 4 * fq, col = h * 64 + c;
;         const f32x4 w0 = *(const f32x4*)(P.w0 + col), a0 = *(const f32x4*)(P.a0 + col), ka = *(const f32x4*)(P.k_a + col);
;         f32x4 wv, bv, kd, av;
; #pragma unroll
;         for (int i = 0; i < 4; ++i) { const float ic = sigmoidf_(Da[n][i] + a0[i]);
;             wv[i] = __builtin_amdgcn_exp2f(-DECAY_SCALE * 1.4426950408889634f * sigmoidf_(Dw[n][i] + w0[i]));
;             const float kk = kk4[n][i] * rs; av[i] = -kk; bv[i] = kk * ic; kd[i] = k4[n][i] * (1.0f + (ic - 1.0f) * ka[i]); }
;         *(LAS f32x4*)(lw + fr * 64 + c) = av; *(LAS f32x4*)(lw + 3072 + fr * 64 + c) = wv; *(LAS f32x4*)(lw + (MODE == 3 ? 1024 : 4096) + fr * 64 + c) = bv;
;         if (MODE != 1) *(f32x4*)(srow + 192 + c) = kd;
;         { LAS float* xsel = (fr == (d ? 15 : 0)) ? lw + 2048 + c : lw + 2304 + lane * 4;
;           if (MODE != 1) *(LAS f32x4*)(xsel + 128) = kd; }
;         if (MODE == 2) { const f32x4 rk = *(const f32x4*)(P.r_k + col); const f32x4 t = r4[n] * kd * rk; bp += (t.x + t.y) + (t.z + t.w); }
;         if ((n & 1) == 1) asm volatile("" ::: "memory");
;     }
;     if (MODE == 2) { bp += shx(bp, 16, lane); bp += shx(bp, 32, lane); if (fq == 0) bon[(size_t)m * 8 + h] = 0.5f * bp; }
	v_pk_mul_f32 v[108:109], v[162:163], v[124:125] op_sel_hi:[1,0]
	v_mul_f32_e32 v98, 0xbf60028a, v98
	v_mul_f32_e32 v99, 0xbf60028a, v99
	v_pk_mul_f32 v[110:111], v[156:157], v[124:125] op_sel_hi:[1,0]
	v_exp_f32_e32 v96, v96
	v_exp_f32_e32 v97, v97
	v_xor_b32_e32 v105, 0x80000000, v109
	v_xor_b32_e32 v104, 0x80000000, v108
	v_exp_f32_e32 v98, v98
	v_exp_f32_e32 v99, v99
	v_xor_b32_e32 v106, 0x80000000, v110
	v_xor_b32_e32 v107, 0x80000000, v111
	v_pk_mul_f32 v[108:109], v[108:109], v[100:101]
	v_pk_mul_f32 v[110:111], v[110:111], v[102:103]
	v_pk_add_f32 v[102:103], v[102:103], -1.0 op_sel_hi:[1,0]
	v_pk_add_f32 v[100:101], v[100:101], -1.0 op_sel_hi:[1,0]
	v_pk_fma_f32 v[70:71], v[204:205], v[102:103], 1.0 op_sel_hi:[1,1,0]
	v_pk_fma_f32 v[68:69], v[202:203], v[100:101], 1.0 op_sel_hi:[1,1,0]
	v_pk_mul_f32 v[70:71], v[142:143], v[70:71]
	v_pk_mul_f32 v[68:69], v[144:145], v[68:69]
	ds_write_b128 v114, v[104:107] offset:64
	ds_write_b128 v114, v[96:99] offset:12352
	ds_write_b128 v114, v[108:111] offset:16448
	global_store_dwordx4 v[140:141], v[68:71], off offset:832
	s_nop 0
	v_pk_mul_f32 v[66:67], v[66:67], v[70:71]
	v_pk_mul_f32 v[64:65], v[64:65], v[68:69]
	ds_write_b128 v186, v[68:71] offset:512
	v_pk_mul_f32 v[66:67], v[118:119], v[66:67]
	v_pk_mul_f32 v[64:65], v[116:117], v[64:65]
	s_nop 0
	v_add_f32_e32 v64, v64, v65
	v_add_f32_e32 v65, v66, v67
	v_add_f32_e32 v64, v64, v65
	v_add_f32_e32 v100, v115, v64
	s_nop 0
	s_nop 0
	s_nop 0
	v_add_f32_e32 v68, v88, v214
	v_add_f32_e32 v69, v89, v215
	v_add_f32_e32 v70, v90, v216
	v_add_f32_e32 v71, v91, v217
	v_add_f32_e32 v92, v92, v228
	v_mul_f32_e32 v68, 0xbfb8aa3b, v68
	v_add_f32_e32 v88, v93, v229
	v_mul_f32_e32 v69, 0xbfb8aa3b, v69
	v_add_f32_e32 v94, v94, v230
	v_mul_f32_e32 v70, 0xbfb8aa3b, v70
	v_add_f32_e32 v90, v95, v231
	v_mul_f32_e32 v71, 0xbfb8aa3b, v71
	v_mul_f32_e32 v92, 0xbfb8aa3b, v92
	v_exp_f32_e32 v68, v68
	v_mul_f32_e32 v88, 0xbfb8aa3b, v88
	v_exp_f32_e32 v69, v69
	v_mul_f32_e32 v94, 0xbfb8aa3b, v94
	v_exp_f32_e32 v70, v70
	v_mul_f32_e32 v90, 0xbfb8aa3b, v90
	v_exp_f32_e32 v71, v71
	v_exp_f32_e32 v92, v92
	v_exp_f32_e32 v88, v88
	v_exp_f32_e32 v94, v94
	v_exp_f32_e32 v90, v90
	v_add_f32_e32 v68, 1.0, v68
	v_add_f32_e32 v69, 1.0, v69
	v_add_f32_e32 v70, 1.0, v70
	v_add_f32_e32 v71, 1.0, v71
	v_add_f32_e32 v92, 1.0, v92
	v_rcp_f32_e32 v68, v68
	v_add_f32_e32 v88, 1.0, v88
	v_rcp_f32_e32 v69, v69
	v_add_f32_e32 v94, 1.0, v94
	v_rcp_f32_e32 v70, v70
	v_add_f32_e32 v90, 1.0, v90
	v_rcp_f32_e32 v71, v71
	v_rcp_f32_e32 v96, v92
	v_rcp_f32_e32 v97, v88
	v_rcp_f32_e32 v98, v94
	v_rcp_f32_e32 v99, v90
	v_mul_f32_e32 v68, 0xbf60028a, v68
	v_mul_f32_e32 v69, 0xbf60028a, v69
	v_pk_mul_f32 v[92:93], v[172:173], v[124:125] op_sel_hi:[1,0]
	v_mul_f32_e32 v70, 0xbf60028a, v70
	v_mul_f32_e32 v71, 0xbf60028a, v71
	v_pk_mul_f32 v[94:95], v[168:169], v[124:125] op_sel_hi:[1,0]
	v_exp_f32_e32 v68, v68
	v_exp_f32_e32 v69, v69
	v_xor_b32_e32 v89, 0x80000000, v93
	v_xor_b32_e32 v88, 0x80000000, v92
	v_exp_f32_e32 v70, v70
	v_exp_f32_e32 v71, v71
	v_xor_b32_e32 v90, 0x80000000, v94
	v_xor_b32_e32 v91, 0x80000000, v95
	v_pk_mul_f32 v[92:93], v[92:93], v[96:97]
	v_pk_mul_f32 v[94:95], v[94:95], v[98:99]
	v_pk_add_f32 v[98:99], v[98:99], -1.0 op_sel_hi:[1,0]
	v_pk_add_f32 v[96:97], v[96:97], -1.0 op_sel_hi:[1,0]
	v_pk_fma_f32 v[66:67], v[234:235], v[98:99], 1.0 op_sel_hi:[1,1,0]
	v_pk_fma_f32 v[64:65], v[232:233], v[96:97], 1.0 op_sel_hi:[1,1,0]
	v_pk_mul_f32 v[66:67], v[146:147], v[66:67]
	v_pk_mul_f32 v[64:65], v[148:149], v[64:65]
	ds_write_b128 v114, v[88:91] offset:128
	ds_write_b128 v114, v[68:71] offset:12416
	ds_write_b128 v114, v[92:95] offset:16512
	global_store_dwordx4 v[140:141], v[64:67], off offset:896
	s_nop 0
	ds_write_b128 v189, v[64:67] offset:512
	v_pk_mul_f32 v[66:67], v[78:79], v[66:67]
	v_pk_mul_f32 v[64:65], v[76:77], v[64:65]
	v_pk_mul_f32 v[66:67], v[152:153], v[66:67]
	v_pk_mul_f32 v[64:65], v[150:151], v[64:65]
	s_nop 0
	v_add_f32_e32 v64, v64, v65
	v_add_f32_e32 v65, v66, v67
	v_add_f32_e32 v64, v64, v65
	v_add_f32_e32 v76, v100, v64
	s_nop 0
	s_nop 0
	s_nop 0
	v_add_f32_e32 v68, v80, v240
	v_add_f32_e32 v69, v81, v241
	v_add_f32_e32 v70, v82, v242
	v_add_f32_e32 v71, v83, v243
	v_mul_f32_e32 v68, 0xbfb8aa3b, v68
	v_mul_f32_e32 v69, 0xbfb8aa3b, v69
	v_mul_f32_e32 v70, 0xbfb8aa3b, v70
	v_mul_f32_e32 v71, 0xbfb8aa3b, v71
	v_exp_f32_e32 v68, v68
	v_exp_f32_e32 v69, v69
	v_exp_f32_e32 v70, v70
	v_exp_f32_e32 v71, v71
	v_add_f32_e32 v68, 1.0, v68
	v_add_f32_e32 v69, 1.0, v69
	v_add_f32_e32 v70, 1.0, v70
	v_add_f32_e32 v71, 1.0, v71
	v_rcp_f32_e32 v92, v68
	v_add_f32_e32 v68, v84, v244
	v_rcp_f32_e32 v93, v69
	v_add_f32_e32 v69, v85, v245
	v_rcp_f32_e32 v88, v70
	v_add_f32_e32 v70, v86, v246
	v_rcp_f32_e32 v89, v71
	v_add_f32_e32 v71, v87, v247
	v_mul_f32_e32 v68, 0xbfb8aa3b, v68
	v_mul_f32_e32 v69, 0xbfb8aa3b, v69
	v_mul_f32_e32 v70, 0xbfb8aa3b, v70
	v_mul_f32_e32 v71, 0xbfb8aa3b, v71
	v_exp_f32_e32 v68, v68
	v_exp_f32_e32 v69, v69
	v_exp_f32_e32 v70, v70
	v_exp_f32_e32 v71, v71
	v_add_f32_e32 v68, 1.0, v68
	v_add_f32_e32 v69, 1.0, v69
	v_add_f32_e32 v70, 1.0, v70
	v_add_f32_e32 v71, 1.0, v71
	v_rcp_f32_e32 v68, v68
	v_rcp_f32_e32 v69, v69
	v_rcp_f32_e32 v70, v70
	v_rcp_f32_e32 v71, v71
	v_mul_f32_e32 v68, 0xbf60028a, v68
	v_mul_f32_e32 v69, 0xbf60028a, v69
	v_pk_mul_f32 v[84:85], v[176:177], v[124:125] op_sel_hi:[1,0]
	v_mul_f32_e32 v70, 0xbf60028a, v70
	v_mul_f32_e32 v71, 0xbf60028a, v71
	v_pk_mul_f32 v[86:87], v[174:175], v[124:125] op_sel_hi:[1,0]
	v_exp_f32_e32 v68, v68
	v_exp_f32_e32 v69, v69
	v_xor_b32_e32 v79, 0x80000000, v85
	v_xor_b32_e32 v78, 0x80000000, v84
	v_exp_f32_e32 v70, v70
	v_exp_f32_e32 v71, v71
	v_xor_b32_e32 v80, 0x80000000, v86
	v_xor_b32_e32 v81, 0x80000000, v87
	v_pk_mul_f32 v[82:83], v[84:85], v[92:93]
	v_pk_mul_f32 v[84:85], v[86:87], v[88:89]
	v_pk_add_f32 v[86:87], v[88:89], -1.0 op_sel_hi:[1,0]
	v_pk_add_f32 v[88:89], v[92:93], -1.0 op_sel_hi:[1,0]
	v_pk_fma_f32 v[66:67], v[238:239], v[86:87], 1.0 op_sel_hi:[1,1,0]
	v_pk_fma_f32 v[64:65], v[236:237], v[88:89], 1.0 op_sel_hi:[1,1,0]
	v_pk_mul_f32 v[66:67], v[158:159], v[66:67]
	v_pk_mul_f32 v[64:65], v[160:161], v[64:65]
	ds_write_b128 v114, v[78:81] offset:192
	ds_write_b128 v114, v[68:71] offset:12480
	ds_write_b128 v114, v[82:85] offset:16576
	global_store_dwordx4 v[140:141], v[64:67], off offset:960
	s_nop 0
	ds_write_b128 v192, v[64:67] offset:512
	v_pk_mul_f32 v[66:67], v[74:75], v[66:67]
	v_pk_mul_f32 v[64:65], v[72:73], v[64:65]
	v_pk_mul_f32 v[66:67], v[166:167], v[66:67]
	v_pk_mul_f32 v[64:65], v[164:165], v[64:65]
	s_nop 0
	v_add_f32_e32 v64, v64, v65
	v_add_f32_e32 v65, v66, v67
	v_add_f32_e32 v64, v64, v65
	v_add_f32_e32 v64, v76, v64
	ds_bpermute_b32 v65, v191, v64
	s_waitcnt lgkmcnt(0)
	v_add_f32_e32 v64, v64, v65
	ds_bpermute_b32 v65, v190, v64
	s_and_saveexec_b64 s[4:5], vcc
	s_cbranch_execz .LBB0_551
; #define LAS __attribute__((address_space(3)))
; __device__ __forceinline__ float shx(float v, int o, int lane) { return __builtin_bit_cast(float, __builtin_amdgcn_ds_bpermute((lane ^ o) << 2, __builtin_bit_cast(int, v))); }
; #define LDS_WAIT() asm volatile("s_waitcnt lgkmcnt(0)" ::: "memory")
; #define lane LANE_()
; template <int MODE>
; __device__ __forceinline__ void scan_prologue(const ScanP& P, int m0, int seqbase, int T, int h, int d, float* slab, LAS float* lw, float* bon, int lane) {
;     ...
;     if (MODE == 2) { bp += shx(bp, 16, lane); bp += shx(bp, 32, lane); if (fq == 0) bon[(size_t)m * 8 + h] = 0.5f * bp; }
; template <int MODE>
; __device__ __forceinline__ void scan_item(const CAS Args* A, int l, int item, float* slab0, LAS float* ldsw, int lane) {
;     ...
;         LDS_WAIT();
;         float nw[1], nb[1], nk[1], nv[1];
;         { const LAS float* xl = ldsw + 2048 + lane; nw[0] = 0.f; nb[0] = 0.f; nk[0] = 0.f; nv[0] = 0.f; if (MODE != 1) { nk[0] = xl[128]; nv[0] = xl[192]; } }
	s_waitcnt lgkmcnt(0)
	v_add_f32_e32 v64, v64, v65
	v_mul_f32_e32 v66, 0.5, v64
	v_lshlrev_b64 v[64:65], 5, v[138:139]
	v_lshl_add_u64 v[64:65], s[80:81], 0, v[64:65]
	global_store_dword v[64:65], v66, off
.LBB0_551:
	s_or_b64 exec, exec, s[4:5]
	s_waitcnt lgkmcnt(0)
	s_waitcnt lgkmcnt(0)
	ds_read2st64_b32 v[64:65], v129 offset0:34 offset1:35
	v_subrev_u32_e32 v240, s94, v129
	v_and_b32_e32 v241, 0xc0, v240
	v_and_b32_e32 v240, 60, v240
	v_add_u32_e32 v240, s94, v240
	v_sub_u32_e32 v236, 0, v241
	v_ashrrev_i32_e32 v237, 31, v236
	ds_read_b32 v228, v240 offset:8704
	ds_read_b32 v229, v240 offset:8768
	ds_read_b32 v230, v240 offset:8832
	ds_read_b32 v231, v240 offset:8896
	s_mov_b32 s4, 0
	s_mov_b32 s5, 15
	s_setprio 1

; __device__ __forceinline__ unsigned pk2(float lo, float hi) { const f2 v = {lo, hi}; return __builtin_bit_cast(unsigned, __builtin_convertvector(v, bf16x2_hw)); }
; __device__ __forceinline__ float shx(float v, int o, int lane) { return __builtin_bit_cast(float, __builtin_amdgcn_ds_bpermute((lane ^ o) << 2, __builtin_bit_cast(int, v))); }
; #define lane LANE_()
; __device__ __forceinline__ float wave_sum(float v, int lane) {
; #pragma unroll
;     for (int o = 1; o < 64; o <<= 1) v += shx(v, o, lane);
;     return v;
; }
; __device__ __forceinline__ void norm_phase(const float* xp, const float* xs, const float* g, const float* modl  , bf16* XN, int wave, int lane, int G) {
;     ...
;     for (int m = gw; m < MT; m += NGW) {
;         const float* xrow = m < MP ? xp + (size_t)m * D : xs + (size_t)(m - MP) * D;
;         const f32x4* xr = (const f32x4*)xrow + lane;
;         f32x4 v[4]; float s = 0.f;
; #pragma unroll
;         for (int j = 0; j < 4; ++j) { v[j] = xr[64 * j]; s += (v[j].x * v[j].x + v[j].y * v[j].y) + (v[j].z * v[j].z + v[j].w * v[j].w); }
;         const float rstd = __builtin_amdgcn_rsqf(wave_sum(s, lane) * (1.f / D) + NORM_EPS);
;         const float* mp = modl + (size_t)seq_of(m) * 12288;
;         unsigned long long* o8 = (unsigned long long*)(XN + (size_t)m * D) + lane;
; #pragma unroll
;         for (int j = 0; j < 4; ++j) { const f32x4 sh = ((const f32x4*)mp)[64 * j + lane], sc = ((const f32x4*)(mp + 1024))[64 * j + lane];
;             const f32x4 y = v[j] * rstd * gv[j] * (1.0f + sc) + sh;
;             o8[64 * j] = (unsigned long long)pk2(y.x, y.y) | ((unsigned long long)pk2(y.z, y.w) << 32); }
;     }
.LBB0_749:
	v_lshl_add_u64 v[24:25], s[56:57], 0, v[34:35]
	global_load_dwordx4 v[20:23], v[24:25], off offset:1024
	global_load_dwordx4 v[16:19], v[24:25], off offset:3072
	global_load_dwordx4 v[70:73], v[24:25], off offset:2048
	global_load_dwordx4 v[28:31], v[24:25], off
	s_nop 0
	s_nop 0
	s_nop 0
	s_nop 0
	s_lshr_b32 s14, s14, 12
	s_add_i32 s14, s14, 1
	s_and_b64 s[24:25], s[54:55], exec
	s_cselect_b32 s14, 0, s14
	s_mul_hi_u32 s25, s14, 0xc000
	s_mul_i32 s14, s14, 0xc000
	s_add_u32 s24, s44, s14
	s_addc_u32 s25, s46, s25
	v_lshl_add_u64 v[40:41], s[24:25], 0, v[34:35]
	global_load_dwordx4 v[52:55], v[40:41], off
	global_load_dwordx4 v[74:77], v[40:41], off offset:1024
	global_load_dwordx4 v[78:81], v[40:41], off offset:2048
	global_load_dwordx4 v[82:85], v[40:41], off offset:3072
	v_add_co_u32_e32 v36, vcc, s26, v40
	s_lshl_b64 s[24:25], s[52:53], 11
	s_nop 0
	v_addc_co_u32_e32 v37, vcc, 0, v41, vcc
	global_load_dwordx4 v[48:51], v[36:37], off
	s_nop 0
	s_add_u32 s10, s10, s8
	s_addc_u32 s11, s11, s9
	s_add_u32 s4, s4, s6
	s_addc_u32 s5, s5, s7
	s_cmp_lt_i32 s10, 0x14000
	s_waitcnt vmcnt(5)
	v_pk_mul_f32 v[36:37], v[30:31], v[30:31]
	v_pk_mul_f32 v[56:57], v[28:29], v[28:29]
	v_pk_mul_f32 v[58:59], v[22:23], v[22:23]
	v_pk_mul_f32 v[60:61], v[20:21], v[20:21]
	v_pk_mov_b32 v[64:65], v[56:57], v[36:37] op_sel:[1,0]
	v_mov_b32_e32 v57, v37
	v_pk_mov_b32 v[36:37], v[60:61], v[58:59] op_sel:[1,0]
	v_mov_b32_e32 v61, v59
	v_mul_f32_e32 v38, v71, v71
	v_mul_f32_e32 v62, v73, v73
	v_pk_add_f32 v[56:57], v[64:65], v[56:57]
	v_pk_add_f32 v[36:37], v[36:37], v[60:61]
	v_mul_f32_e32 v47, v16, v16
	v_mul_f32_e32 v66, v17, v17
	v_mul_f32_e32 v67, v18, v18
	v_mul_f32_e32 v68, v19, v19
	v_pk_fma_f32 v[58:59], v[70:71], v[70:71], v[38:39] op_sel_hi:[1,1,0]
	v_pk_fma_f32 v[62:63], v[72:73], v[72:73], v[62:63] op_sel_hi:[1,1,0]
	v_pk_add_f32 v[56:57], v[56:57], v[56:57] op_sel:[0,1] op_sel_hi:[1,0]
	v_pk_add_f32 v[36:37], v[36:37], v[36:37] op_sel:[0,1] op_sel_hi:[1,0]
	v_mov_b32_e32 v59, v67
	v_mov_b32_e32 v63, v68
	v_mov_b32_e32 v57, v47
	v_mov_b32_e32 v37, v66
	v_pk_add_f32 v[58:59], v[58:59], v[62:63]
	v_pk_add_f32 v[36:37], v[56:57], v[36:37]
	s_waitcnt vmcnt(0)
	v_pk_add_f32 v[50:51], v[50:51], 1.0 op_sel_hi:[1,0]
	v_pk_add_f32 v[36:37], v[36:37], v[58:59]
	v_pk_add_f32 v[48:49], v[48:49], 1.0 op_sel_hi:[1,0]
	v_add_f32_e32 v36, v36, v37
	v_lshl_add_u64 v[56:57], v[40:41], 0, s[20:21]
	global_load_dwordx4 v[58:61], v[56:57], off offset:1024
	global_load_dwordx4 v[62:65], v[56:57], off offset:2048
	global_load_dwordx4 v[66:69], v[56:57], off offset:3072
	s_nop 1
	v_add_f32_dpp v36, v36, v36 quad_perm:[1,0,3,2] row_mask:0xf bank_mask:0xf
	s_nop 1
	v_add_f32_dpp v36, v36, v36 quad_perm:[2,3,0,1] row_mask:0xf bank_mask:0xf
	s_nop 1
	v_add_f32_dpp v36, v36, v36 row_half_mirror row_mask:0xf bank_mask:0xf
	s_nop 1
	v_add_f32_dpp v36, v36, v36 row_mirror row_mask:0xf bank_mask:0xf
	s_nop 1
	v_add_f32_dpp v36, v36, v36 row_bcast:15 row_mask:0xa bank_mask:0xf
	s_nop 1
	v_add_f32_dpp v36, v36, v36 row_bcast:31 row_mask:0xc bank_mask:0xf
	s_nop 1
	v_readlane_b32 s98, v36, 63
	s_nop 1
	v_mov_b32_e32 v38, s98
	v_lshl_add_u64 v[36:37], v[32:33], 0, s[24:25]
	v_fmamk_f32 v38, v38, 0x3a800000, v218
	v_rsq_f32_e32 v38, v38
	s_nop 0
	v_pk_mul_f32 v[30:31], v[30:31], v[38:39] op_sel_hi:[1,0]
	v_pk_mul_f32 v[28:29], v[28:29], v[38:39] op_sel_hi:[1,0]
	v_pk_mul_f32 v[30:31], v[2:3], v[30:31]
	v_pk_mul_f32 v[28:29], v[0:1], v[28:29]
	v_pk_fma_f32 v[30:31], v[50:51], v[30:31], v[54:55]
	v_pk_fma_f32 v[28:29], v[48:49], v[28:29], v[52:53]
	v_pk_mul_f32 v[22:23], v[22:23], v[38:39] op_sel_hi:[1,0]
	v_cvt_pk_bf16_f32 v28, v28, v29
	v_cvt_pk_bf16_f32 v29, v30, v31
	global_store_dwordx2 v[36:37], v[28:29], off
	s_nop 0
	s_nop 0
	s_nop 0
	v_pk_mul_f32 v[20:21], v[20:21], v[38:39] op_sel_hi:[1,0]
	v_pk_mul_f32 v[22:23], v[6:7], v[22:23]
	v_pk_mul_f32 v[20:21], v[4:5], v[20:21]
	v_pk_mul_f32 v[26:27], v[72:73], v[38:39] op_sel_hi:[1,0]
	v_pk_mul_f32 v[24:25], v[70:71], v[38:39] op_sel_hi:[1,0]
	v_pk_mul_f32 v[26:27], v[10:11], v[26:27]
	v_pk_mul_f32 v[24:25], v[8:9], v[24:25]
	v_pk_mul_f32 v[18:19], v[18:19], v[38:39] op_sel_hi:[1,0]
	v_pk_mul_f32 v[16:17], v[16:17], v[38:39] op_sel_hi:[1,0]
	v_pk_mul_f32 v[18:19], v[14:15], v[18:19]
	v_pk_mul_f32 v[16:17], v[12:13], v[16:17]
	s_waitcnt vmcnt(3)
	v_pk_add_f32 v[30:31], v[60:61], 1.0 op_sel_hi:[1,0]
	v_pk_add_f32 v[28:29], v[58:59], 1.0 op_sel_hi:[1,0]
	v_pk_fma_f32 v[22:23], v[30:31], v[22:23], v[76:77]
	v_pk_fma_f32 v[20:21], v[28:29], v[20:21], v[74:75]
	s_nop 0
	v_cvt_pk_bf16_f32 v20, v20, v21
	v_cvt_pk_bf16_f32 v21, v22, v23
	global_store_dwordx2 v[36:37], v[20:21], off offset:512
	s_nop 0
	s_nop 0
	s_nop 0
	s_waitcnt vmcnt(3)
	v_pk_add_f32 v[22:23], v[64:65], 1.0 op_sel_hi:[1,0]
	v_pk_add_f32 v[20:21], v[62:63], 1.0 op_sel_hi:[1,0]
	v_pk_fma_f32 v[22:23], v[22:23], v[26:27], v[80:81]
	v_pk_fma_f32 v[20:21], v[20:21], v[24:25], v[78:79]
	s_nop 0
	v_cvt_pk_bf16_f32 v20, v20, v21
	v_cvt_pk_bf16_f32 v21, v22, v23
	global_store_dwordx2 v[36:37], v[20:21], off offset:1024
	s_nop 0
	s_nop 0
	s_nop 0
	s_waitcnt vmcnt(3)
	v_pk_add_f32 v[22:23], v[68:69], 1.0 op_sel_hi:[1,0]
	v_pk_add_f32 v[20:21], v[66:67], 1.0 op_sel_hi:[1,0]
	v_pk_fma_f32 v[18:19], v[18:19], v[22:23], v[84:85]
	v_pk_fma_f32 v[16:17], v[16:17], v[20:21], v[82:83]
	s_nop 0
	v_cvt_pk_bf16_f32 v16, v16, v17
	v_cvt_pk_bf16_f32 v17, v18, v19
	global_store_dwordx2 v[36:37], v[16:17], off offset:1536
	s_cbranch_scc0 .LBB0_754

; __global__ void __launch_bounds__(NWAVES * 64, 2) hymba_fwd(Args args_unused) {
	.amdhsa_kernel _Z9hymba_fwd4Args
		.amdhsa_group_segment_fixed_size 0
		.amdhsa_private_segment_fixed_size 0
		.amdhsa_kernarg_size 472
		.amdhsa_user_sgpr_count 2
		.amdhsa_user_sgpr_dispatch_ptr 0
		.amdhsa_user_sgpr_queue_ptr 0
		.amdhsa_user_sgpr_kernarg_segment_ptr 1
		.amdhsa_user_sgpr_dispatch_id 0
		.amdhsa_user_sgpr_kernarg_preload_length 0
		.amdhsa_user_sgpr_kernarg_preload_offset 0
		.amdhsa_user_sgpr_private_segment_size 0
		.amdhsa_uses_dynamic_stack 0
		.amdhsa_enable_private_segment 0
		.amdhsa_system_sgpr_workgroup_id_x 1
		.amdhsa_system_sgpr_workgroup_id_y 0
		.amdhsa_system_sgpr_workgroup_id_z 0
		.amdhsa_system_sgpr_workgroup_info 0
		.amdhsa_system_vgpr_workitem_id 0
		.amdhsa_next_free_vgpr 256
		.amdhsa_next_free_sgpr 100
		.amdhsa_accum_offset 256
		.amdhsa_reserve_vcc 1
		.amdhsa_float_round_mode_32 0
		.amdhsa_float_round_mode_16_64 0
		.amdhsa_float_denorm_mode_32 3
		.amdhsa_float_denorm_mode_16_64 3
		.amdhsa_dx10_clamp 1
		.amdhsa_ieee_mode 1
		.amdhsa_fp16_overflow 0
		.amdhsa_tg_split 0
		.amdhsa_exception_fp_ieee_invalid_op 0
		.amdhsa_exception_fp_denorm_src 0
		.amdhsa_exception_fp_ieee_div_zero 0
		.amdhsa_exception_fp_ieee_overflow 0
		.amdhsa_exception_fp_ieee_underflow 0
		.amdhsa_exception_fp_ieee_inexact 0
		.amdhsa_exception_int_div_zero 0
	.end_amdhsa_kernel

; __global__ void __launch_bounds__(NWAVES * 64, 2) hymba_fwd(Args args_unused) {
amdhsa.kernels:
  - .agpr_count:     0
    .args:
      - .offset:         0
        .size:           216
        .value_kind:     by_value
      - .offset:         216
        .size:           4
        .value_kind:     hidden_block_count_x
      - .offset:         220
        .size:           4
        .value_kind:     hidden_block_count_y
      - .offset:         224
        .size:           4
        .value_kind:     hidden_block_count_z
      - .offset:         228
        .size:           2
        .value_kind:     hidden_group_size_x
      - .offset:         230
        .size:           2
        .value_kind:     hidden_group_size_y
      - .offset:         232
        .size:           2
        .value_kind:     hidden_group_size_z
      - .offset:         234
        .size:           2
        .value_kind:     hidden_remainder_x
      - .offset:         236
        .size:           2
        .value_kind:     hidden_remainder_y
      - .offset:         238
        .size:           2
        .value_kind:     hidden_remainder_z
      - .offset:         256
        .size:           8
        .value_kind:     hidden_global_offset_x
      - .offset:         264
        .size:           8
        .value_kind:     hidden_global_offset_y
      - .offset:         272
        .size:           8
        .value_kind:     hidden_global_offset_z
      - .offset:         280
        .size:           2
        .value_kind:     hidden_grid_dims
      - .offset:         336
        .size:           4
        .value_kind:     hidden_dynamic_lds_size
    .group_segment_fixed_size: 0
    .kernarg_segment_align: 8
    .kernarg_segment_size: 472
    .language:       OpenCL C
    .language_version:
      - 2
      - 0
    .max_flat_workgroup_size: 512
    .name:           _Z9hymba_fwd4Args
    .private_segment_fixed_size: 0
    .sgpr_count:     106
    .sgpr_spill_count: 24
    .symbol:         _Z9hymba_fwd4Args.kd
    .uniform_work_group_size: 1
    .uses_dynamic_stack: false
    .vgpr_count:     256
    .vgpr_spill_count: 0
    .wavefront_size: 64
